# compression phase rewritten by hand: one item per workgroup on 8 waves, token rows and per-wave W1T slices staged through XOR-swizzled LDS with coalesced loads (was fragment-shaped loads), exact-erf g
# speedup vs baseline: 1.0095x; 1.0095x over previous
; DI int my_tid() { int t = threadIdx.x & 255; asm volatile("" : "+v"(t)); return t; }
; DI int vb_id() { return (int)blockIdx.x + half_id() * (int)gridDim.x; }
; DI int vb_n() { return (int)gridDim.x * 2; }
; DI void phase_compress(const Params& p, char* smem) {
;   char* ws = p.ws;
;   const u16* KC = (const u16*)(ws + WS_KC);
;   const u16* VC = (const u16*)(ws + WS_VC);
;   const u16* WT = (const u16*)(ws + WS_WT_C1);
;   u16* KCMP = (u16*)(ws + WS_KCMP);
;   u16* VCMPT = (u16*)(ws + WS_VCMPT);
;   float* Hs = (float*)smem;
;   const int tid = my_tid(), lane = tid & 63, wave = tid >> 6;
;   const int lr = lane & 31, hh = lane >> 5;
;   for (int it = vb_id(); it < 128; it += vb_n()) {
;     const int kv = it & 1, mt = it >> 1;
;     const u16* SRC = kv ? VC : KC;
;     const float* pe = kv ? p.pe_v : p.pe_k;
;     int mi = mt * 32 + lr;
;     int bg = mi >> 8, n = mi & 255;
;     if (n > 254) n = 254;
;     const u16* arow = SRC + ((size_t)((bg >> 1) * 4096 + 16 * n)) * 128 + (bg & 1) * 64 + hh * 8;
;     const u16* brow0 = WT + ((size_t)(kv * 64 + lr)) * 2048 + hh * 8;
;     const u16* brow1 = brow0 + (size_t)32 * 2048;
.LBB0_267:
	s_or_b64 exec, exec, s[0:1]
	s_add_u32 s62, s86, 0x9a40200
	v_readfirstlane_b32 s0, v211
	s_addc_u32 s63, s87, 0
	s_lshr_b32 s0, s0, 8
	s_mul_i32 s0, s0, s54
	s_add_i32 s20, s0, s52
	v_mov_b32_e32 v0, v210
	s_cmpk_lt_i32 s20, 0x80
	s_waitcnt lgkmcnt(0)
	s_barrier
	s_lshl_b32 s88, s54, 1
	s_cmp_gt_u32 s52, 127
	s_cbranch_scc1 .Lcp_done
	s_mov_b32 s10, s52
	s_and_b32 s11, s10, 1
	s_lshr_b32 s12, s10, 1
	v_readfirstlane_b32 s13, v211
	v_mbcnt_lo_u32_b32 v0, -1, 0
	v_mbcnt_hi_u32_b32 v0, -1, v0
	s_nop 3
	s_lshr_b32 s14, s13, 6
	v_and_b32_e32 v1, 31, v0
	v_lshrrev_b32_e32 v2, 5, v0
	s_mov_b32 s20, 0x378e98ab
	s_mov_b32 s21, 0x3b7cd369
	s_mov_b32 s22, 0xbcc618b2
	s_mov_b32 s23, 0x3dda74e4
	s_mov_b32 s24, 0x3f228afd
	s_mov_b32 s25, 0x3e03c728
	s_mov_b32 s26, 0xbfb8aa3b
	s_mov_b32 s27, 0x42ce8ed0
	s_mov_b32 s28, 0xc2b17218
	s_mov_b32 s29, 0x7fffffff
	s_cmp_eq_u32 s11, 0
	s_cbranch_scc0 .Lcp_v
	s_add_u32 s0, s86, 0x8200200
	s_addc_u32 s1, s87, 0
	v_readlane_b32 s2, v253, 6
	v_readlane_b32 s3, v253, 7
	v_readlane_b32 s6, v253, 12
	v_readlane_b32 s7, v253, 13
	s_add_u32 s4, s86, 0x1100000
	s_addc_u32 s5, s87, 0
	s_add_u32 s8, s86, 0x9a00200
	s_addc_u32 s9, s87, 0
	s_branch .Lcp_ptr
.Lcp_v:
	s_add_u32 s0, s86, 0x8600200
	s_addc_u32 s1, s87, 0
	v_readlane_b32 s2, v253, 8
	v_readlane_b32 s3, v253, 9
	v_readlane_b32 s6, v253, 16
	v_readlane_b32 s7, v253, 17
	s_add_u32 s4, s86, 0x1140000
	s_addc_u32 s5, s87, 0
	s_add_u32 s8, s86, 0x9a40200
	s_addc_u32 s9, s87, 0
.Lcp_ptr:
	s_nop 3
	s_add_u32 s16, s4, 0x20000
	s_addc_u32 s17, s5, 0
	v_lshlrev_b32_e32 v236, 5, v211
	global_load_dwordx4 v[168:171], v236, s[6:7]
	global_load_dwordx4 v[172:175], v236, s[6:7] offset:16
	s_lshl_b32 s13, s12, 5
	s_and_b32 s30, s13, 0xff
	s_lshr_b32 s13, s12, 3
	s_and_b32 s15, s13, 1
	s_lshr_b32 s13, s13, 1
	s_lshl_b32 s13, s13, 12
	s_lshl_b32 s31, s30, 4
	s_add_u32 s31, s31, s13
	s_lshl_b32 s31, s31, 8
	s_lshl_b32 s15, s15, 7
	s_add_u32 s31, s31, s15
	s_add_u32 s0, s0, s31
	s_addc_u32 s1, s1, 0
	v_add_u32_e32 v8, 0, v211
	v_lshrrev_b32_e32 v9, 3, v8
	v_min_u32_e32 v9, 0x20f, v9
	v_and_b32_e32 v10, 7, v8
	v_lshlrev_b32_e32 v11, 8, v9
	v_lshl_add_u32 v11, v10, 4, v11
	global_load_dwordx4 v[48:51], v11, s[0:1]
	v_bfe_u32 v12, v9, 7, 1
	v_xor_b32_e32 v12, v12, v9
	v_bfe_u32 v13, v9, 4, 3
	v_xor_b32_e32 v13, v13, v10
	v_lshlrev_b32_e32 v12, 7, v12
	v_lshl_add_u32 v176, v13, 4, v12
	v_add_u32_e32 v8, 512, v211
	v_lshrrev_b32_e32 v9, 3, v8
	v_min_u32_e32 v9, 0x20f, v9
	v_and_b32_e32 v10, 7, v8
	v_lshlrev_b32_e32 v11, 8, v9
	v_lshl_add_u32 v11, v10, 4, v11
	global_load_dwordx4 v[52:55], v11, s[0:1]
	v_bfe_u32 v12, v9, 7, 1
	v_xor_b32_e32 v12, v12, v9
	v_bfe_u32 v13, v9, 4, 3
	v_xor_b32_e32 v13, v13, v10
	v_lshlrev_b32_e32 v12, 7, v12
	v_lshl_add_u32 v177, v13, 4, v12
	v_add_u32_e32 v8, 1024, v211
	v_lshrrev_b32_e32 v9, 3, v8
	v_min_u32_e32 v9, 0x20f, v9
	v_and_b32_e32 v10, 7, v8
	v_lshlrev_b32_e32 v11, 8, v9
	v_lshl_add_u32 v11, v10, 4, v11
	global_load_dwordx4 v[56:59], v11, s[0:1]
	v_bfe_u32 v12, v9, 7, 1
	v_xor_b32_e32 v12, v12, v9
	v_bfe_u32 v13, v9, 4, 3
	v_xor_b32_e32 v13, v13, v10
	v_lshlrev_b32_e32 v12, 7, v12
	v_lshl_add_u32 v178, v13, 4, v12
	v_add_u32_e32 v8, 1536, v211
	v_lshrrev_b32_e32 v9, 3, v8
	v_min_u32_e32 v9, 0x20f, v9
	v_and_b32_e32 v10, 7, v8
	v_lshlrev_b32_e32 v11, 8, v9
	v_lshl_add_u32 v11, v10, 4, v11
	global_load_dwordx4 v[60:63], v11, s[0:1]
	v_bfe_u32 v12, v9, 7, 1
	v_xor_b32_e32 v12, v12, v9
	v_bfe_u32 v13, v9, 4, 3
	v_xor_b32_e32 v13, v13, v10
	v_lshlrev_b32_e32 v12, 7, v12
	v_lshl_add_u32 v179, v13, 4, v12
	v_add_u32_e32 v8, 2048, v211
	v_lshrrev_b32_e32 v9, 3, v8
	v_min_u32_e32 v9, 0x20f, v9
	v_and_b32_e32 v10, 7, v8
	v_lshlrev_b32_e32 v11, 8, v9
	v_lshl_add_u32 v11, v10, 4, v11
	global_load_dwordx4 v[64:67], v11, s[0:1]
	v_bfe_u32 v12, v9, 7, 1
	v_xor_b32_e32 v12, v12, v9
	v_bfe_u32 v13, v9, 4, 3
	v_xor_b32_e32 v13, v13, v10
	v_lshlrev_b32_e32 v12, 7, v12
	v_lshl_add_u32 v180, v13, 4, v12
	v_add_u32_e32 v8, 2560, v211
	v_lshrrev_b32_e32 v9, 3, v8
	v_min_u32_e32 v9, 0x20f, v9
	v_and_b32_e32 v10, 7, v8
	v_lshlrev_b32_e32 v11, 8, v9
	v_lshl_add_u32 v11, v10, 4, v11
	global_load_dwordx4 v[68:71], v11, s[0:1]
	v_bfe_u32 v12, v9, 7, 1
	v_xor_b32_e32 v12, v12, v9
	v_bfe_u32 v13, v9, 4, 3
	v_xor_b32_e32 v13, v13, v10
	v_lshlrev_b32_e32 v12, 7, v12
	v_lshl_add_u32 v181, v13, 4, v12
	v_add_u32_e32 v8, 3072, v211
	v_lshrrev_b32_e32 v9, 3, v8
	v_min_u32_e32 v9, 0x20f, v9
	v_and_b32_e32 v10, 7, v8
	v_lshlrev_b32_e32 v11, 8, v9
	v_lshl_add_u32 v11, v10, 4, v11
	global_load_dwordx4 v[72:75], v11, s[0:1]
	v_bfe_u32 v12, v9, 7, 1
	v_xor_b32_e32 v12, v12, v9
	v_bfe_u32 v13, v9, 4, 3
	v_xor_b32_e32 v13, v13, v10
	v_lshlrev_b32_e32 v12, 7, v12
	v_lshl_add_u32 v182, v13, 4, v12
	v_add_u32_e32 v8, 3584, v211
	v_lshrrev_b32_e32 v9, 3, v8
	v_min_u32_e32 v9, 0x20f, v9
	v_and_b32_e32 v10, 7, v8
	v_lshlrev_b32_e32 v11, 8, v9
	v_lshl_add_u32 v11, v10, 4, v11
	global_load_dwordx4 v[76:79], v11, s[0:1]
	v_bfe_u32 v12, v9, 7, 1
	v_xor_b32_e32 v12, v12, v9
	v_bfe_u32 v13, v9, 4, 3
	v_xor_b32_e32 v13, v13, v10
	v_lshlrev_b32_e32 v12, 7, v12
	v_lshl_add_u32 v183, v13, 4, v12
	v_add_u32_e32 v8, 4096, v211
	v_lshrrev_b32_e32 v9, 3, v8
	v_min_u32_e32 v9, 0x20f, v9
	v_and_b32_e32 v10, 7, v8
	v_lshlrev_b32_e32 v11, 8, v9
	v_lshl_add_u32 v11, v10, 4, v11
	global_load_dwordx4 v[80:83], v11, s[0:1]
	v_bfe_u32 v12, v9, 7, 1
	v_xor_b32_e32 v12, v12, v9
	v_bfe_u32 v13, v9, 4, 3
	v_xor_b32_e32 v13, v13, v10
	v_lshlrev_b32_e32 v12, 7, v12
	v_lshl_add_u32 v184, v13, 4, v12
	v_add_u32_e32 v8, s30, v1
	v_min_u32_e32 v8, 0xfe, v8
	v_subrev_u32_e32 v8, s30, v8
	s_lshr_b32 s13, s14, 2
; DI void phase_compress(const Params& p, char* smem) {
;     ...
;     int mi = mt * 32 + lr;
;     int bg = mi >> 8, n = mi & 255;
;     if (n > 254) n = 254;
;     const u16* arow = SRC + ((size_t)((bg >> 1) * 4096 + 16 * n)) * 128 + (bg & 1) * 64 + hh * 8;
;     const u16* brow0 = WT + ((size_t)(kv * 64 + lr)) * 2048 + hh * 8;
;     const u16* brow1 = brow0 + (size_t)32 * 2048;
;     f32x16 acc0, acc1;
; #pragma unroll
;     for (int e = 0; e < 16; ++e) { acc0[e] = 0.f; acc1[e] = 0.f; }
; #pragma unroll 4
;     for (int sI = 0; sI < 32; ++sI) {
;       const int s_ = wave * 32 + sI;
;       const int l = s_ >> 2, d0 = (s_ & 3) * 16;
;       u32x4 ar = *(const u32x4*)(arow + l * 128 + d0);
;       float4 p0 = *(const float4*)(pe + l * 64 + d0 + hh * 8);
;       float4 p1 = *(const float4*)(pe + l * 64 + d0 + hh * 8 + 4);
;       bf16x8 b0 = *(const bf16x8*)(brow0 + s_ * 16);
;       bf16x8 b1 = *(const bf16x8*)(brow1 + s_ * 16);
	v_add_u32_e32 v9, s13, v8
	v_and_b32_e32 v10, 7, v9
	v_bfe_u32 v11, v9, 3, 1
	s_lshl_b32 s13, s14, 2
	v_xor_b32_e32 v12, s13, v11
	v_xor_b32_e32 v12, 0, v12
	v_lshl_add_u32 v12, v8, 4, v12
	v_lshlrev_b32_e32 v201, 7, v12
	v_add_u32_e32 v201, 64, v201
	v_xor_b32_e32 v12, s13, v11
	v_xor_b32_e32 v12, 1, v12
	v_lshl_add_u32 v12, v8, 4, v12
	v_lshlrev_b32_e32 v202, 7, v12
	v_add_u32_e32 v202, 64, v202
	v_xor_b32_e32 v12, s13, v11
	v_xor_b32_e32 v12, 2, v12
	v_lshl_add_u32 v12, v8, 4, v12
	v_lshlrev_b32_e32 v203, 7, v12
	v_add_u32_e32 v203, 64, v203
	v_xor_b32_e32 v12, s13, v11
	v_xor_b32_e32 v12, 3, v12
	v_lshl_add_u32 v12, v8, 4, v12
	v_lshlrev_b32_e32 v204, 7, v12
	v_add_u32_e32 v204, 64, v204
	v_xor_b32_e32 v12, 0, v2
	v_xor_b32_e32 v13, v12, v10
	v_lshlrev_b32_e32 v205, 4, v13
	v_and_b32_e32 v14, 7, v1
	v_xor_b32_e32 v13, v12, v14
	v_lshlrev_b32_e32 v216, 4, v13
	v_xor_b32_e32 v12, 2, v2
	v_xor_b32_e32 v13, v12, v10
	v_lshlrev_b32_e32 v206, 4, v13
	v_and_b32_e32 v14, 7, v1
	v_xor_b32_e32 v13, v12, v14
	v_lshlrev_b32_e32 v217, 4, v13
	v_xor_b32_e32 v12, 4, v2
	v_xor_b32_e32 v13, v12, v10
	v_lshlrev_b32_e32 v207, 4, v13
	v_and_b32_e32 v14, 7, v1
	v_xor_b32_e32 v13, v12, v14
	v_lshlrev_b32_e32 v218, 4, v13
	v_xor_b32_e32 v12, 6, v2
	v_xor_b32_e32 v13, v12, v10
	v_lshlrev_b32_e32 v208, 4, v13
	v_and_b32_e32 v14, 7, v1
	v_xor_b32_e32 v13, v12, v14
	v_lshlrev_b32_e32 v219, 4, v13
	v_bfe_u32 v12, v1, 3, 1
	v_xor_b32_e32 v12, v12, v1
	v_lshlrev_b32_e32 v220, 7, v12
	s_lshl_b32 s13, s14, 13
	s_add_u32 s13, s13, 67904
	v_add_u32_e32 v220, s13, v220
	v_add_u32_e32 v8, 0, v0
	v_lshrrev_b32_e32 v9, 3, v8
	v_and_b32_e32 v10, 7, v8
	v_lshlrev_b32_e32 v193, 12, v9
	v_lshl_add_u32 v193, v10, 4, v193
	s_lshl_b32 s15, s14, 9
	v_add_u32_e32 v193, s15, v193
	v_bfe_u32 v11, v9, 3, 1
	v_xor_b32_e32 v11, v11, v9
	v_and_b32_e32 v12, 7, v9
	v_xor_b32_e32 v12, v12, v10
	v_lshlrev_b32_e32 v11, 7, v11
	v_lshl_add_u32 v11, v12, 4, v11
	v_add_u32_e32 v185, s13, v11
	v_add_u32_e32 v8, 64, v0
	v_lshrrev_b32_e32 v9, 3, v8
	v_and_b32_e32 v10, 7, v8
	v_lshlrev_b32_e32 v194, 12, v9
	v_lshl_add_u32 v194, v10, 4, v194
	s_lshl_b32 s15, s14, 9
	v_add_u32_e32 v194, s15, v194
	v_bfe_u32 v11, v9, 3, 1
	v_xor_b32_e32 v11, v11, v9
	v_and_b32_e32 v12, 7, v9
	v_xor_b32_e32 v12, v12, v10
	v_lshlrev_b32_e32 v11, 7, v11
	v_lshl_add_u32 v11, v12, 4, v11
	v_add_u32_e32 v186, s13, v11
	v_add_u32_e32 v8, 128, v0
	v_lshrrev_b32_e32 v9, 3, v8
	v_and_b32_e32 v10, 7, v8
	v_lshlrev_b32_e32 v195, 12, v9
	v_lshl_add_u32 v195, v10, 4, v195
	s_lshl_b32 s15, s14, 9
	v_add_u32_e32 v195, s15, v195
	v_bfe_u32 v11, v9, 3, 1
	v_xor_b32_e32 v11, v11, v9
	v_and_b32_e32 v12, 7, v9
	v_xor_b32_e32 v12, v12, v10
	v_lshlrev_b32_e32 v11, 7, v11
	v_lshl_add_u32 v11, v12, 4, v11
	v_add_u32_e32 v187, s13, v11
	v_add_u32_e32 v8, 192, v0
	v_lshrrev_b32_e32 v9, 3, v8
	v_and_b32_e32 v10, 7, v8
	v_lshlrev_b32_e32 v196, 12, v9
	v_lshl_add_u32 v196, v10, 4, v196
	s_lshl_b32 s15, s14, 9
	v_add_u32_e32 v196, s15, v196
	v_bfe_u32 v11, v9, 3, 1
	v_xor_b32_e32 v11, v11, v9
	v_and_b32_e32 v12, 7, v9
	v_xor_b32_e32 v12, v12, v10
	v_lshlrev_b32_e32 v11, 7, v11
	v_lshl_add_u32 v11, v12, 4, v11
	v_add_u32_e32 v188, s13, v11
	v_add_u32_e32 v8, 256, v0
	v_lshrrev_b32_e32 v9, 3, v8
	v_and_b32_e32 v10, 7, v8
	v_lshlrev_b32_e32 v197, 12, v9
	v_lshl_add_u32 v197, v10, 4, v197
	s_lshl_b32 s15, s14, 9
	v_add_u32_e32 v197, s15, v197
	v_bfe_u32 v11, v9, 3, 1
	v_xor_b32_e32 v11, v11, v9
	v_and_b32_e32 v12, 7, v9
	v_xor_b32_e32 v12, v12, v10
	v_lshlrev_b32_e32 v11, 7, v11
	v_lshl_add_u32 v11, v12, 4, v11
	v_add_u32_e32 v189, s13, v11
	v_add_u32_e32 v8, 320, v0
	v_lshrrev_b32_e32 v9, 3, v8
	v_and_b32_e32 v10, 7, v8
	v_lshlrev_b32_e32 v198, 12, v9
	v_lshl_add_u32 v198, v10, 4, v198
	s_lshl_b32 s15, s14, 9
	v_add_u32_e32 v198, s15, v198
	v_bfe_u32 v11, v9, 3, 1
	v_xor_b32_e32 v11, v11, v9
	v_and_b32_e32 v12, 7, v9
	v_xor_b32_e32 v12, v12, v10
	v_lshlrev_b32_e32 v11, 7, v11
	v_lshl_add_u32 v11, v12, 4, v11
	v_add_u32_e32 v190, s13, v11
	v_add_u32_e32 v8, 384, v0
	v_lshrrev_b32_e32 v9, 3, v8
	v_and_b32_e32 v10, 7, v8
	v_lshlrev_b32_e32 v199, 12, v9
	v_lshl_add_u32 v199, v10, 4, v199
	s_lshl_b32 s15, s14, 9
	v_add_u32_e32 v199, s15, v199
	v_bfe_u32 v11, v9, 3, 1
	v_xor_b32_e32 v11, v11, v9
	v_and_b32_e32 v12, 7, v9
	v_xor_b32_e32 v12, v12, v10
	v_lshlrev_b32_e32 v11, 7, v11
	v_lshl_add_u32 v11, v12, 4, v11
	v_add_u32_e32 v191, s13, v11
	v_add_u32_e32 v8, 448, v0
	v_lshrrev_b32_e32 v9, 3, v8
	v_and_b32_e32 v10, 7, v8
	v_lshlrev_b32_e32 v200, 12, v9
	v_lshl_add_u32 v200, v10, 4, v200
	s_lshl_b32 s15, s14, 9
	v_add_u32_e32 v200, s15, v200
	v_bfe_u32 v11, v9, 3, 1
	v_xor_b32_e32 v11, v11, v9
	v_and_b32_e32 v12, 7, v9
	v_xor_b32_e32 v12, v12, v10
	v_lshlrev_b32_e32 v11, 7, v11
	v_lshl_add_u32 v11, v12, 4, v11
	v_add_u32_e32 v192, s13, v11
	global_load_dwordx4 v[132:135], v193, s[4:5] offset:0
	global_load_dwordx4 v[136:139], v194, s[4:5] offset:0
	global_load_dwordx4 v[140:143], v195, s[4:5] offset:0
	global_load_dwordx4 v[144:147], v196, s[4:5] offset:0
	global_load_dwordx4 v[148:151], v197, s[4:5] offset:0
	global_load_dwordx4 v[152:155], v198, s[4:5] offset:0
	global_load_dwordx4 v[156:159], v199, s[4:5] offset:0
	global_load_dwordx4 v[160:163], v200, s[4:5] offset:0
	s_lshl_b32 s15, s14, 10
	v_lshlrev_b32_e32 v5, 5, v2
	v_add_u32_e32 v5, s15, v5
	s_mul_i32 s15, s14, 8320
	v_mul_u32_u24_e32 v7, 1040, v2
	v_lshl_add_u32 v7, v1, 2, v7
	v_add_u32_e32 v7, s15, v7
	v_add_u32_e32 v7, 64, v7
	v_mov_b32_e32 v16, 0
	v_mov_b32_e32 v17, 0
	v_mov_b32_e32 v18, 0
	v_mov_b32_e32 v19, 0
	v_mov_b32_e32 v20, 0
	v_mov_b32_e32 v21, 0
	v_mov_b32_e32 v22, 0
	v_mov_b32_e32 v23, 0
	v_mov_b32_e32 v24, 0
	v_mov_b32_e32 v25, 0
	v_mov_b32_e32 v26, 0
	v_mov_b32_e32 v27, 0
	v_mov_b32_e32 v28, 0
	v_mov_b32_e32 v29, 0
	v_mov_b32_e32 v30, 0
	v_mov_b32_e32 v31, 0
	v_mov_b32_e32 v32, 0
	v_mov_b32_e32 v33, 0
	v_mov_b32_e32 v34, 0
	v_mov_b32_e32 v35, 0
	v_mov_b32_e32 v36, 0
	v_mov_b32_e32 v37, 0
	v_mov_b32_e32 v38, 0
	v_mov_b32_e32 v39, 0
	v_mov_b32_e32 v40, 0
	v_mov_b32_e32 v41, 0
	v_mov_b32_e32 v42, 0
	v_mov_b32_e32 v43, 0
	v_mov_b32_e32 v44, 0
	v_mov_b32_e32 v45, 0
	v_mov_b32_e32 v46, 0
	v_mov_b32_e32 v47, 0
	v_add_u32_e32 v251, 141760, v236
	s_waitcnt vmcnt(17)
; #define MFMA32(a, b, c) __builtin_amdgcn_mfma_f32_32x32x16_bf16((a), (b), (c), 0, 0, 0)
; DI float bflo(unsigned u) { return __uint_as_float(u << 16); }
; DI float bfhi(unsigned u) { return __uint_as_float(u & 0xffff0000u); }
; DI void phase_compress(const Params& p, char* smem) {
;     ...
; #pragma unroll 4
;     for (int sI = 0; sI < 32; ++sI) {
;       const int s_ = wave * 32 + sI;
;       const int l = s_ >> 2, d0 = (s_ & 3) * 16;
;       u32x4 ar = *(const u32x4*)(arow + l * 128 + d0);
;       float4 p0 = *(const float4*)(pe + l * 64 + d0 + hh * 8);
;       float4 p1 = *(const float4*)(pe + l * 64 + d0 + hh * 8 + 4);
;       bf16x8 b0 = *(const bf16x8*)(brow0 + s_ * 16);
;       bf16x8 b1 = *(const bf16x8*)(brow1 + s_ * 16);
;       u32x4 aw;
;       aw[0] = pack2(bflo(ar[0]) + p0.x, bfhi(ar[0]) + p0.y);
;       aw[1] = pack2(bflo(ar[1]) + p0.z, bfhi(ar[1]) + p0.w);
;       aw[2] = pack2(bflo(ar[2]) + p1.x, bfhi(ar[2]) + p1.y);
;       aw[3] = pack2(bflo(ar[3]) + p1.z, bfhi(ar[3]) + p1.w);
;       bf16x8 a = __builtin_bit_cast(bf16x8, aw);
;       acc0 = MFMA32(a, b0, acc0);
;       acc1 = MFMA32(a, b1, acc1);
;     }
	ds_write_b128 v251, v[168:171]
	ds_write_b128 v251, v[172:175] offset:16
	s_waitcnt vmcnt(16)
	v_add_u32_e32 v176, 64, v176
	ds_write_b128 v176, v[48:51]
	s_waitcnt vmcnt(15)
	v_add_u32_e32 v177, 64, v177
	ds_write_b128 v177, v[52:55]
	s_waitcnt vmcnt(14)
	v_add_u32_e32 v178, 64, v178
	ds_write_b128 v178, v[56:59]
	s_waitcnt vmcnt(13)
	v_add_u32_e32 v179, 64, v179
	ds_write_b128 v179, v[60:63]
	s_waitcnt vmcnt(12)
	v_add_u32_e32 v180, 64, v180
	ds_write_b128 v180, v[64:67]
	s_waitcnt vmcnt(11)
	v_add_u32_e32 v181, 64, v181
	ds_write_b128 v181, v[68:71]
	s_waitcnt vmcnt(10)
	v_add_u32_e32 v182, 64, v182
	ds_write_b128 v182, v[72:75]
	s_waitcnt vmcnt(9)
	v_add_u32_e32 v183, 64, v183
	ds_write_b128 v183, v[76:79]
	s_waitcnt vmcnt(8)
	v_add_u32_e32 v184, 64, v184
	ds_write_b128 v184, v[80:83]
	s_waitcnt vmcnt(7)
	ds_write_b128 v185, v[132:135]
	s_waitcnt vmcnt(6)
	ds_write_b128 v186, v[136:139]
	s_waitcnt vmcnt(5)
	ds_write_b128 v187, v[140:143]
	s_waitcnt vmcnt(4)
	ds_write_b128 v188, v[144:147]
	s_waitcnt vmcnt(3)
	ds_write_b128 v189, v[148:151]
	s_waitcnt vmcnt(2)
	ds_write_b128 v190, v[152:155]
	s_waitcnt vmcnt(1)
	ds_write_b128 v191, v[156:159]
	s_waitcnt vmcnt(0)
	ds_write_b128 v192, v[160:163]
	s_waitcnt lgkmcnt(0)
	s_barrier
	global_load_dwordx4 v[48:51], v5, s[2:3] offset:0
	global_load_dwordx4 v[52:55], v5, s[2:3] offset:16
	global_load_dwordx4 v[56:59], v5, s[2:3] offset:64
	global_load_dwordx4 v[60:63], v5, s[2:3] offset:80
	global_load_dwordx4 v[64:67], v5, s[2:3] offset:128
	global_load_dwordx4 v[68:71], v5, s[2:3] offset:144
	global_load_dwordx4 v[72:75], v5, s[2:3] offset:192
	global_load_dwordx4 v[76:79], v5, s[2:3] offset:208
	global_load_dwordx4 v[132:135], v193, s[4:5] offset:128
	global_load_dwordx4 v[136:139], v194, s[4:5] offset:128
	global_load_dwordx4 v[140:143], v195, s[4:5] offset:128
	global_load_dwordx4 v[144:147], v196, s[4:5] offset:128
	global_load_dwordx4 v[148:151], v197, s[4:5] offset:128
	global_load_dwordx4 v[152:155], v198, s[4:5] offset:128
	global_load_dwordx4 v[156:159], v199, s[4:5] offset:128
	global_load_dwordx4 v[160:163], v200, s[4:5] offset:128
	v_add_u32_e32 v221, v201, v205
	v_add_u32_e32 v222, v220, v216
	ds_read_b128 v[88:91], v221
	ds_read_b128 v[92:95], v222
	ds_read_b128 v[100:103], v222 offset:4096
	v_add_u32_e32 v221, v201, v206
	v_add_u32_e32 v222, v220, v217
	ds_read_b128 v[104:107], v221
	ds_read_b128 v[108:111], v222
	ds_read_b128 v[112:115], v222 offset:4096
	s_waitcnt vmcnt(14) lgkmcnt(3)
	v_lshlrev_b32_e32 v224, 16, v88
	v_and_b32_e32 v225, 0xffff0000, v88
	v_lshlrev_b32_e32 v226, 16, v89
	v_and_b32_e32 v227, 0xffff0000, v89
	v_lshlrev_b32_e32 v228, 16, v90
	v_and_b32_e32 v229, 0xffff0000, v90
	v_lshlrev_b32_e32 v230, 16, v91
	v_and_b32_e32 v231, 0xffff0000, v91
	v_pk_add_f32 v[224:225], v[224:225], v[48:49]
	v_pk_add_f32 v[226:227], v[226:227], v[50:51]
	v_pk_add_f32 v[228:229], v[228:229], v[52:53]
	v_pk_add_f32 v[230:231], v[230:231], v[54:55]
	v_cvt_pk_bf16_f32 v232, v224, v225
	v_cvt_pk_bf16_f32 v233, v226, v227
	v_cvt_pk_bf16_f32 v234, v228, v229
	v_cvt_pk_bf16_f32 v235, v230, v231
	s_nop 1
	v_mfma_f32_32x32x16_bf16 v[16:31], v[232:235], v[92:95], v[16:31]
	v_mfma_f32_32x32x16_bf16 v[32:47], v[232:235], v[100:103], v[32:47]
	v_add_u32_e32 v221, v201, v207
	v_add_u32_e32 v222, v220, v218
	ds_read_b128 v[88:91], v221
	ds_read_b128 v[92:95], v222
	ds_read_b128 v[100:103], v222 offset:4096
	s_waitcnt vmcnt(12) lgkmcnt(3)
	v_lshlrev_b32_e32 v224, 16, v104
	v_and_b32_e32 v225, 0xffff0000, v104
	v_lshlrev_b32_e32 v226, 16, v105
	v_and_b32_e32 v227, 0xffff0000, v105
	v_lshlrev_b32_e32 v228, 16, v106
	v_and_b32_e32 v229, 0xffff0000, v106
	v_lshlrev_b32_e32 v230, 16, v107
	v_and_b32_e32 v231, 0xffff0000, v107
	v_pk_add_f32 v[224:225], v[224:225], v[56:57]
	v_pk_add_f32 v[226:227], v[226:227], v[58:59]
	v_pk_add_f32 v[228:229], v[228:229], v[60:61]
	v_pk_add_f32 v[230:231], v[230:231], v[62:63]
	v_cvt_pk_bf16_f32 v232, v224, v225
	v_cvt_pk_bf16_f32 v233, v226, v227
	v_cvt_pk_bf16_f32 v234, v228, v229
	v_cvt_pk_bf16_f32 v235, v230, v231
	s_nop 1
	v_mfma_f32_32x32x16_bf16 v[16:31], v[232:235], v[108:111], v[16:31]
	v_mfma_f32_32x32x16_bf16 v[32:47], v[232:235], v[112:115], v[32:47]
	v_add_u32_e32 v221, v201, v208
	v_add_u32_e32 v222, v220, v219
	ds_read_b128 v[104:107], v221
	ds_read_b128 v[108:111], v222
	ds_read_b128 v[112:115], v222 offset:4096
	s_waitcnt vmcnt(10) lgkmcnt(3)
	v_lshlrev_b32_e32 v224, 16, v88
	v_and_b32_e32 v225, 0xffff0000, v88
	v_lshlrev_b32_e32 v226, 16, v89
	v_and_b32_e32 v227, 0xffff0000, v89
	v_lshlrev_b32_e32 v228, 16, v90
	v_and_b32_e32 v229, 0xffff0000, v90
	v_lshlrev_b32_e32 v230, 16, v91
	v_and_b32_e32 v231, 0xffff0000, v91
	v_pk_add_f32 v[224:225], v[224:225], v[64:65]
	v_pk_add_f32 v[226:227], v[226:227], v[66:67]
	v_pk_add_f32 v[228:229], v[228:229], v[68:69]
	v_pk_add_f32 v[230:231], v[230:231], v[70:71]
	v_cvt_pk_bf16_f32 v232, v224, v225
	v_cvt_pk_bf16_f32 v233, v226, v227
	v_cvt_pk_bf16_f32 v234, v228, v229
	v_cvt_pk_bf16_f32 v235, v230, v231
	s_nop 1
	v_mfma_f32_32x32x16_bf16 v[16:31], v[232:235], v[92:95], v[16:31]
	v_mfma_f32_32x32x16_bf16 v[32:47], v[232:235], v[100:103], v[32:47]
	s_waitcnt vmcnt(8) lgkmcnt(0)
	v_lshlrev_b32_e32 v224, 16, v104
	v_and_b32_e32 v225, 0xffff0000, v104
	v_lshlrev_b32_e32 v226, 16, v105
	v_and_b32_e32 v227, 0xffff0000, v105
	v_lshlrev_b32_e32 v228, 16, v106
	v_and_b32_e32 v229, 0xffff0000, v106
	v_lshlrev_b32_e32 v230, 16, v107
	v_and_b32_e32 v231, 0xffff0000, v107
	v_pk_add_f32 v[224:225], v[224:225], v[72:73]
	v_pk_add_f32 v[226:227], v[226:227], v[74:75]
	v_pk_add_f32 v[228:229], v[228:229], v[76:77]
	v_pk_add_f32 v[230:231], v[230:231], v[78:79]
	v_cvt_pk_bf16_f32 v232, v224, v225
	v_cvt_pk_bf16_f32 v233, v226, v227
	v_cvt_pk_bf16_f32 v234, v228, v229
	v_cvt_pk_bf16_f32 v235, v230, v231
	s_nop 1
	v_mfma_f32_32x32x16_bf16 v[16:31], v[232:235], v[108:111], v[16:31]
	v_mfma_f32_32x32x16_bf16 v[32:47], v[232:235], v[112:115], v[32:47]
	s_waitcnt vmcnt(0)
; #define MFMA32(a, b, c) __builtin_amdgcn_mfma_f32_32x32x16_bf16((a), (b), (c), 0, 0, 0)
; DI float bflo(unsigned u) { return __uint_as_float(u << 16); }
; DI float bfhi(unsigned u) { return __uint_as_float(u & 0xffff0000u); }
; DI void phase_compress(const Params& p, char* smem) {
;     ...
; #pragma unroll 4
;     for (int sI = 0; sI < 32; ++sI) {
;       const int s_ = wave * 32 + sI;
;       const int l = s_ >> 2, d0 = (s_ & 3) * 16;
;       u32x4 ar = *(const u32x4*)(arow + l * 128 + d0);
;       float4 p0 = *(const float4*)(pe + l * 64 + d0 + hh * 8);
;       float4 p1 = *(const float4*)(pe + l * 64 + d0 + hh * 8 + 4);
;       bf16x8 b0 = *(const bf16x8*)(brow0 + s_ * 16);
;       bf16x8 b1 = *(const bf16x8*)(brow1 + s_ * 16);
;       u32x4 aw;
;       aw[0] = pack2(bflo(ar[0]) + p0.x, bfhi(ar[0]) + p0.y);
;       aw[1] = pack2(bflo(ar[1]) + p0.z, bfhi(ar[1]) + p0.w);
;       aw[2] = pack2(bflo(ar[2]) + p1.x, bfhi(ar[2]) + p1.y);
;       aw[3] = pack2(bflo(ar[3]) + p1.z, bfhi(ar[3]) + p1.w);
;       bf16x8 a = __builtin_bit_cast(bf16x8, aw);
;       acc0 = MFMA32(a, b0, acc0);
;       acc1 = MFMA32(a, b1, acc1);
;     }
	ds_write_b128 v185, v[132:135]
	ds_write_b128 v186, v[136:139]
	ds_write_b128 v187, v[140:143]
	ds_write_b128 v188, v[144:147]
	ds_write_b128 v189, v[148:151]
	ds_write_b128 v190, v[152:155]
	ds_write_b128 v191, v[156:159]
	ds_write_b128 v192, v[160:163]
	s_waitcnt lgkmcnt(0)
	global_load_dwordx4 v[48:51], v5, s[2:3] offset:256
	global_load_dwordx4 v[52:55], v5, s[2:3] offset:272
	global_load_dwordx4 v[56:59], v5, s[2:3] offset:320
	global_load_dwordx4 v[60:63], v5, s[2:3] offset:336
	global_load_dwordx4 v[64:67], v5, s[2:3] offset:384
	global_load_dwordx4 v[68:71], v5, s[2:3] offset:400
	global_load_dwordx4 v[72:75], v5, s[2:3] offset:448
	global_load_dwordx4 v[76:79], v5, s[2:3] offset:464
	global_load_dwordx4 v[132:135], v193, s[4:5] offset:256
	global_load_dwordx4 v[136:139], v194, s[4:5] offset:256
	global_load_dwordx4 v[140:143], v195, s[4:5] offset:256
	global_load_dwordx4 v[144:147], v196, s[4:5] offset:256
	global_load_dwordx4 v[148:151], v197, s[4:5] offset:256
	global_load_dwordx4 v[152:155], v198, s[4:5] offset:256
	global_load_dwordx4 v[156:159], v199, s[4:5] offset:256
	global_load_dwordx4 v[160:163], v200, s[4:5] offset:256
	v_add_u32_e32 v221, v202, v205
	v_add_u32_e32 v222, v220, v216
	ds_read_b128 v[88:91], v221
	ds_read_b128 v[92:95], v222
	ds_read_b128 v[100:103], v222 offset:4096
	v_add_u32_e32 v221, v202, v206
	v_add_u32_e32 v222, v220, v217
	ds_read_b128 v[104:107], v221
	ds_read_b128 v[108:111], v222
	ds_read_b128 v[112:115], v222 offset:4096
	s_waitcnt vmcnt(14) lgkmcnt(3)
	v_lshlrev_b32_e32 v224, 16, v88
	v_and_b32_e32 v225, 0xffff0000, v88
	v_lshlrev_b32_e32 v226, 16, v89
	v_and_b32_e32 v227, 0xffff0000, v89
	v_lshlrev_b32_e32 v228, 16, v90
	v_and_b32_e32 v229, 0xffff0000, v90
	v_lshlrev_b32_e32 v230, 16, v91
	v_and_b32_e32 v231, 0xffff0000, v91
	v_pk_add_f32 v[224:225], v[224:225], v[48:49]
	v_pk_add_f32 v[226:227], v[226:227], v[50:51]
	v_pk_add_f32 v[228:229], v[228:229], v[52:53]
	v_pk_add_f32 v[230:231], v[230:231], v[54:55]
	v_cvt_pk_bf16_f32 v232, v224, v225
	v_cvt_pk_bf16_f32 v233, v226, v227
	v_cvt_pk_bf16_f32 v234, v228, v229
	v_cvt_pk_bf16_f32 v235, v230, v231
	s_nop 1
	v_mfma_f32_32x32x16_bf16 v[16:31], v[232:235], v[92:95], v[16:31]
	v_mfma_f32_32x32x16_bf16 v[32:47], v[232:235], v[100:103], v[32:47]
	v_add_u32_e32 v221, v202, v207
	v_add_u32_e32 v222, v220, v218
	ds_read_b128 v[88:91], v221
	ds_read_b128 v[92:95], v222
	ds_read_b128 v[100:103], v222 offset:4096
	s_waitcnt vmcnt(12) lgkmcnt(3)
	v_lshlrev_b32_e32 v224, 16, v104
	v_and_b32_e32 v225, 0xffff0000, v104
	v_lshlrev_b32_e32 v226, 16, v105
	v_and_b32_e32 v227, 0xffff0000, v105
	v_lshlrev_b32_e32 v228, 16, v106
	v_and_b32_e32 v229, 0xffff0000, v106
	v_lshlrev_b32_e32 v230, 16, v107
	v_and_b32_e32 v231, 0xffff0000, v107
	v_pk_add_f32 v[224:225], v[224:225], v[56:57]
	v_pk_add_f32 v[226:227], v[226:227], v[58:59]
	v_pk_add_f32 v[228:229], v[228:229], v[60:61]
	v_pk_add_f32 v[230:231], v[230:231], v[62:63]
	v_cvt_pk_bf16_f32 v232, v224, v225
	v_cvt_pk_bf16_f32 v233, v226, v227
	v_cvt_pk_bf16_f32 v234, v228, v229
	v_cvt_pk_bf16_f32 v235, v230, v231
	s_nop 1
	v_mfma_f32_32x32x16_bf16 v[16:31], v[232:235], v[108:111], v[16:31]
	v_mfma_f32_32x32x16_bf16 v[32:47], v[232:235], v[112:115], v[32:47]
	v_add_u32_e32 v221, v202, v208
	v_add_u32_e32 v222, v220, v219
	ds_read_b128 v[104:107], v221
	ds_read_b128 v[108:111], v222
	ds_read_b128 v[112:115], v222 offset:4096
	s_waitcnt vmcnt(10) lgkmcnt(3)
	v_lshlrev_b32_e32 v224, 16, v88
	v_and_b32_e32 v225, 0xffff0000, v88
	v_lshlrev_b32_e32 v226, 16, v89
	v_and_b32_e32 v227, 0xffff0000, v89
	v_lshlrev_b32_e32 v228, 16, v90
	v_and_b32_e32 v229, 0xffff0000, v90
	v_lshlrev_b32_e32 v230, 16, v91
	v_and_b32_e32 v231, 0xffff0000, v91
	v_pk_add_f32 v[224:225], v[224:225], v[64:65]
	v_pk_add_f32 v[226:227], v[226:227], v[66:67]
	v_pk_add_f32 v[228:229], v[228:229], v[68:69]
	v_pk_add_f32 v[230:231], v[230:231], v[70:71]
	v_cvt_pk_bf16_f32 v232, v224, v225
	v_cvt_pk_bf16_f32 v233, v226, v227
	v_cvt_pk_bf16_f32 v234, v228, v229
	v_cvt_pk_bf16_f32 v235, v230, v231
	s_nop 1
	v_mfma_f32_32x32x16_bf16 v[16:31], v[232:235], v[92:95], v[16:31]
	v_mfma_f32_32x32x16_bf16 v[32:47], v[232:235], v[100:103], v[32:47]
	s_waitcnt vmcnt(8) lgkmcnt(0)
	v_lshlrev_b32_e32 v224, 16, v104
	v_and_b32_e32 v225, 0xffff0000, v104
	v_lshlrev_b32_e32 v226, 16, v105
	v_and_b32_e32 v227, 0xffff0000, v105
	v_lshlrev_b32_e32 v228, 16, v106
	v_and_b32_e32 v229, 0xffff0000, v106
	v_lshlrev_b32_e32 v230, 16, v107
	v_and_b32_e32 v231, 0xffff0000, v107
	v_pk_add_f32 v[224:225], v[224:225], v[72:73]
	v_pk_add_f32 v[226:227], v[226:227], v[74:75]
	v_pk_add_f32 v[228:229], v[228:229], v[76:77]
	v_pk_add_f32 v[230:231], v[230:231], v[78:79]
	v_cvt_pk_bf16_f32 v232, v224, v225
	v_cvt_pk_bf16_f32 v233, v226, v227
	v_cvt_pk_bf16_f32 v234, v228, v229
	v_cvt_pk_bf16_f32 v235, v230, v231
	s_nop 1
	v_mfma_f32_32x32x16_bf16 v[16:31], v[232:235], v[108:111], v[16:31]
	v_mfma_f32_32x32x16_bf16 v[32:47], v[232:235], v[112:115], v[32:47]
	s_waitcnt vmcnt(0)
	ds_write_b128 v185, v[132:135]
	ds_write_b128 v186, v[136:139]
	ds_write_b128 v187, v[140:143]
	ds_write_b128 v188, v[144:147]
	ds_write_b128 v189, v[148:151]
	ds_write_b128 v190, v[152:155]
	ds_write_b128 v191, v[156:159]
	ds_write_b128 v192, v[160:163]
	s_waitcnt lgkmcnt(0)
; #define MFMA32(a, b, c) __builtin_amdgcn_mfma_f32_32x32x16_bf16((a), (b), (c), 0, 0, 0)
; DI float bflo(unsigned u) { return __uint_as_float(u << 16); }
; DI float bfhi(unsigned u) { return __uint_as_float(u & 0xffff0000u); }
; DI void phase_compress(const Params& p, char* smem) {
;     ...
; #pragma unroll 4
;     for (int sI = 0; sI < 32; ++sI) {
;       const int s_ = wave * 32 + sI;
;       const int l = s_ >> 2, d0 = (s_ & 3) * 16;
;       u32x4 ar = *(const u32x4*)(arow + l * 128 + d0);
;       float4 p0 = *(const float4*)(pe + l * 64 + d0 + hh * 8);
;       float4 p1 = *(const float4*)(pe + l * 64 + d0 + hh * 8 + 4);
;       bf16x8 b0 = *(const bf16x8*)(brow0 + s_ * 16);
;       bf16x8 b1 = *(const bf16x8*)(brow1 + s_ * 16);
;       u32x4 aw;
;       aw[0] = pack2(bflo(ar[0]) + p0.x, bfhi(ar[0]) + p0.y);
;       aw[1] = pack2(bflo(ar[1]) + p0.z, bfhi(ar[1]) + p0.w);
;       aw[2] = pack2(bflo(ar[2]) + p1.x, bfhi(ar[2]) + p1.y);
;       aw[3] = pack2(bflo(ar[3]) + p1.z, bfhi(ar[3]) + p1.w);
;       bf16x8 a = __builtin_bit_cast(bf16x8, aw);
;       acc0 = MFMA32(a, b0, acc0);
;       acc1 = MFMA32(a, b1, acc1);
;     }
	global_load_dwordx4 v[48:51], v5, s[2:3] offset:512
	global_load_dwordx4 v[52:55], v5, s[2:3] offset:528
	global_load_dwordx4 v[56:59], v5, s[2:3] offset:576
	global_load_dwordx4 v[60:63], v5, s[2:3] offset:592
	global_load_dwordx4 v[64:67], v5, s[2:3] offset:640
	global_load_dwordx4 v[68:71], v5, s[2:3] offset:656
	global_load_dwordx4 v[72:75], v5, s[2:3] offset:704
	global_load_dwordx4 v[76:79], v5, s[2:3] offset:720
	global_load_dwordx4 v[132:135], v193, s[4:5] offset:384
	global_load_dwordx4 v[136:139], v194, s[4:5] offset:384
	global_load_dwordx4 v[140:143], v195, s[4:5] offset:384
	global_load_dwordx4 v[144:147], v196, s[4:5] offset:384
	global_load_dwordx4 v[148:151], v197, s[4:5] offset:384
	global_load_dwordx4 v[152:155], v198, s[4:5] offset:384
	global_load_dwordx4 v[156:159], v199, s[4:5] offset:384
	global_load_dwordx4 v[160:163], v200, s[4:5] offset:384
	v_add_u32_e32 v221, v203, v205
	v_add_u32_e32 v222, v220, v216
	ds_read_b128 v[88:91], v221
	ds_read_b128 v[92:95], v222
	ds_read_b128 v[100:103], v222 offset:4096
	v_add_u32_e32 v221, v203, v206
	v_add_u32_e32 v222, v220, v217
	ds_read_b128 v[104:107], v221
	ds_read_b128 v[108:111], v222
	ds_read_b128 v[112:115], v222 offset:4096
	s_waitcnt vmcnt(14) lgkmcnt(3)
	v_lshlrev_b32_e32 v224, 16, v88
	v_and_b32_e32 v225, 0xffff0000, v88
	v_lshlrev_b32_e32 v226, 16, v89
	v_and_b32_e32 v227, 0xffff0000, v89
	v_lshlrev_b32_e32 v228, 16, v90
	v_and_b32_e32 v229, 0xffff0000, v90
	v_lshlrev_b32_e32 v230, 16, v91
	v_and_b32_e32 v231, 0xffff0000, v91
	v_pk_add_f32 v[224:225], v[224:225], v[48:49]
	v_pk_add_f32 v[226:227], v[226:227], v[50:51]
	v_pk_add_f32 v[228:229], v[228:229], v[52:53]
	v_pk_add_f32 v[230:231], v[230:231], v[54:55]
	v_cvt_pk_bf16_f32 v232, v224, v225
	v_cvt_pk_bf16_f32 v233, v226, v227
	v_cvt_pk_bf16_f32 v234, v228, v229
	v_cvt_pk_bf16_f32 v235, v230, v231
	s_nop 1
	v_mfma_f32_32x32x16_bf16 v[16:31], v[232:235], v[92:95], v[16:31]
	v_mfma_f32_32x32x16_bf16 v[32:47], v[232:235], v[100:103], v[32:47]
	v_add_u32_e32 v221, v203, v207
	v_add_u32_e32 v222, v220, v218
	ds_read_b128 v[88:91], v221
	ds_read_b128 v[92:95], v222
	ds_read_b128 v[100:103], v222 offset:4096
	s_waitcnt vmcnt(12) lgkmcnt(3)
	v_lshlrev_b32_e32 v224, 16, v104
	v_and_b32_e32 v225, 0xffff0000, v104
	v_lshlrev_b32_e32 v226, 16, v105
	v_and_b32_e32 v227, 0xffff0000, v105
	v_lshlrev_b32_e32 v228, 16, v106
	v_and_b32_e32 v229, 0xffff0000, v106
	v_lshlrev_b32_e32 v230, 16, v107
	v_and_b32_e32 v231, 0xffff0000, v107
	v_pk_add_f32 v[224:225], v[224:225], v[56:57]
	v_pk_add_f32 v[226:227], v[226:227], v[58:59]
	v_pk_add_f32 v[228:229], v[228:229], v[60:61]
	v_pk_add_f32 v[230:231], v[230:231], v[62:63]
	v_cvt_pk_bf16_f32 v232, v224, v225
	v_cvt_pk_bf16_f32 v233, v226, v227
	v_cvt_pk_bf16_f32 v234, v228, v229
	v_cvt_pk_bf16_f32 v235, v230, v231
	s_nop 1
	v_mfma_f32_32x32x16_bf16 v[16:31], v[232:235], v[108:111], v[16:31]
	v_mfma_f32_32x32x16_bf16 v[32:47], v[232:235], v[112:115], v[32:47]
	v_add_u32_e32 v221, v203, v208
	v_add_u32_e32 v222, v220, v219
	ds_read_b128 v[104:107], v221
	ds_read_b128 v[108:111], v222
	ds_read_b128 v[112:115], v222 offset:4096
	s_waitcnt vmcnt(10) lgkmcnt(3)
	v_lshlrev_b32_e32 v224, 16, v88
	v_and_b32_e32 v225, 0xffff0000, v88
	v_lshlrev_b32_e32 v226, 16, v89
	v_and_b32_e32 v227, 0xffff0000, v89
	v_lshlrev_b32_e32 v228, 16, v90
	v_and_b32_e32 v229, 0xffff0000, v90
	v_lshlrev_b32_e32 v230, 16, v91
	v_and_b32_e32 v231, 0xffff0000, v91
	v_pk_add_f32 v[224:225], v[224:225], v[64:65]
	v_pk_add_f32 v[226:227], v[226:227], v[66:67]
	v_pk_add_f32 v[228:229], v[228:229], v[68:69]
	v_pk_add_f32 v[230:231], v[230:231], v[70:71]
	v_cvt_pk_bf16_f32 v232, v224, v225
	v_cvt_pk_bf16_f32 v233, v226, v227
	v_cvt_pk_bf16_f32 v234, v228, v229
	v_cvt_pk_bf16_f32 v235, v230, v231
	s_nop 1
	v_mfma_f32_32x32x16_bf16 v[16:31], v[232:235], v[92:95], v[16:31]
	v_mfma_f32_32x32x16_bf16 v[32:47], v[232:235], v[100:103], v[32:47]
	s_waitcnt vmcnt(8) lgkmcnt(0)
	v_lshlrev_b32_e32 v224, 16, v104
	v_and_b32_e32 v225, 0xffff0000, v104
	v_lshlrev_b32_e32 v226, 16, v105
	v_and_b32_e32 v227, 0xffff0000, v105
	v_lshlrev_b32_e32 v228, 16, v106
	v_and_b32_e32 v229, 0xffff0000, v106
	v_lshlrev_b32_e32 v230, 16, v107
	v_and_b32_e32 v231, 0xffff0000, v107
	v_pk_add_f32 v[224:225], v[224:225], v[72:73]
	v_pk_add_f32 v[226:227], v[226:227], v[74:75]
	v_pk_add_f32 v[228:229], v[228:229], v[76:77]
	v_pk_add_f32 v[230:231], v[230:231], v[78:79]
	v_cvt_pk_bf16_f32 v232, v224, v225
	v_cvt_pk_bf16_f32 v233, v226, v227
	v_cvt_pk_bf16_f32 v234, v228, v229
	v_cvt_pk_bf16_f32 v235, v230, v231
	s_nop 1
	v_mfma_f32_32x32x16_bf16 v[16:31], v[232:235], v[108:111], v[16:31]
	v_mfma_f32_32x32x16_bf16 v[32:47], v[232:235], v[112:115], v[32:47]
	s_waitcnt vmcnt(0)
	ds_write_b128 v185, v[132:135]
	ds_write_b128 v186, v[136:139]
	ds_write_b128 v187, v[140:143]
	ds_write_b128 v188, v[144:147]
	ds_write_b128 v189, v[148:151]
	ds_write_b128 v190, v[152:155]
	ds_write_b128 v191, v[156:159]
	ds_write_b128 v192, v[160:163]
	s_waitcnt lgkmcnt(0)
	global_load_dwordx4 v[48:51], v5, s[2:3] offset:768
	global_load_dwordx4 v[52:55], v5, s[2:3] offset:784
	global_load_dwordx4 v[56:59], v5, s[2:3] offset:832
	global_load_dwordx4 v[60:63], v5, s[2:3] offset:848
	global_load_dwordx4 v[64:67], v5, s[2:3] offset:896
	global_load_dwordx4 v[68:71], v5, s[2:3] offset:912
	global_load_dwordx4 v[72:75], v5, s[2:3] offset:960
	global_load_dwordx4 v[76:79], v5, s[2:3] offset:976
	v_add_u32_e32 v221, v204, v205
	v_add_u32_e32 v222, v220, v216
	ds_read_b128 v[88:91], v221
	ds_read_b128 v[92:95], v222
	ds_read_b128 v[100:103], v222 offset:4096
	v_add_u32_e32 v221, v204, v206
	v_add_u32_e32 v222, v220, v217
	ds_read_b128 v[104:107], v221
	ds_read_b128 v[108:111], v222
	ds_read_b128 v[112:115], v222 offset:4096
	s_waitcnt vmcnt(6) lgkmcnt(3)
; #define MFMA32(a, b, c) __builtin_amdgcn_mfma_f32_32x32x16_bf16((a), (b), (c), 0, 0, 0)
; DI void hsync() { hsync_impl(false); }
; DI float bflo(unsigned u) { return __uint_as_float(u << 16); }
; DI float bfhi(unsigned u) { return __uint_as_float(u & 0xffff0000u); }
; DI int crow(int i, int hh) { return (i & 3) + 8 * (i >> 2) + 4 * hh; }
; DI void phase_compress(const Params& p, char* smem) {
;     ...
; #pragma unroll 4
;     for (int sI = 0; sI < 32; ++sI) {
;       const int s_ = wave * 32 + sI;
;       const int l = s_ >> 2, d0 = (s_ & 3) * 16;
;       u32x4 ar = *(const u32x4*)(arow + l * 128 + d0);
;       float4 p0 = *(const float4*)(pe + l * 64 + d0 + hh * 8);
;       float4 p1 = *(const float4*)(pe + l * 64 + d0 + hh * 8 + 4);
;       bf16x8 b0 = *(const bf16x8*)(brow0 + s_ * 16);
;       bf16x8 b1 = *(const bf16x8*)(brow1 + s_ * 16);
;       u32x4 aw;
;       aw[0] = pack2(bflo(ar[0]) + p0.x, bfhi(ar[0]) + p0.y);
;       aw[1] = pack2(bflo(ar[1]) + p0.z, bfhi(ar[1]) + p0.w);
;       aw[2] = pack2(bflo(ar[2]) + p1.x, bfhi(ar[2]) + p1.y);
;       aw[3] = pack2(bflo(ar[3]) + p1.z, bfhi(ar[3]) + p1.w);
;       bf16x8 a = __builtin_bit_cast(bf16x8, aw);
;       acc0 = MFMA32(a, b0, acc0);
;       acc1 = MFMA32(a, b1, acc1);
;     }
;     hsync();
; #pragma unroll
;     for (int e = 0; e < 16; ++e) {
;       Hs[(wave * 32 + crow(e, hh)) * 65 + lr] = acc0[e];
;       Hs[(wave * 32 + crow(e, hh)) * 65 + 32 + lr] = acc1[e];
;     }
;     hsync();
	v_lshlrev_b32_e32 v224, 16, v88
	v_and_b32_e32 v225, 0xffff0000, v88
	v_lshlrev_b32_e32 v226, 16, v89
	v_and_b32_e32 v227, 0xffff0000, v89
	v_lshlrev_b32_e32 v228, 16, v90
	v_and_b32_e32 v229, 0xffff0000, v90
	v_lshlrev_b32_e32 v230, 16, v91
	v_and_b32_e32 v231, 0xffff0000, v91
	v_pk_add_f32 v[224:225], v[224:225], v[48:49]
	v_pk_add_f32 v[226:227], v[226:227], v[50:51]
	v_pk_add_f32 v[228:229], v[228:229], v[52:53]
	v_pk_add_f32 v[230:231], v[230:231], v[54:55]
	v_cvt_pk_bf16_f32 v232, v224, v225
	v_cvt_pk_bf16_f32 v233, v226, v227
	v_cvt_pk_bf16_f32 v234, v228, v229
	v_cvt_pk_bf16_f32 v235, v230, v231
	s_nop 1
	v_mfma_f32_32x32x16_bf16 v[16:31], v[232:235], v[92:95], v[16:31]
	v_mfma_f32_32x32x16_bf16 v[32:47], v[232:235], v[100:103], v[32:47]
	v_add_u32_e32 v221, v204, v207
	v_add_u32_e32 v222, v220, v218
	ds_read_b128 v[88:91], v221
	ds_read_b128 v[92:95], v222
	ds_read_b128 v[100:103], v222 offset:4096
	s_waitcnt vmcnt(4) lgkmcnt(3)
	v_lshlrev_b32_e32 v224, 16, v104
	v_and_b32_e32 v225, 0xffff0000, v104
	v_lshlrev_b32_e32 v226, 16, v105
	v_and_b32_e32 v227, 0xffff0000, v105
	v_lshlrev_b32_e32 v228, 16, v106
	v_and_b32_e32 v229, 0xffff0000, v106
	v_lshlrev_b32_e32 v230, 16, v107
	v_and_b32_e32 v231, 0xffff0000, v107
	v_pk_add_f32 v[224:225], v[224:225], v[56:57]
	v_pk_add_f32 v[226:227], v[226:227], v[58:59]
	v_pk_add_f32 v[228:229], v[228:229], v[60:61]
	v_pk_add_f32 v[230:231], v[230:231], v[62:63]
	v_cvt_pk_bf16_f32 v232, v224, v225
	v_cvt_pk_bf16_f32 v233, v226, v227
	v_cvt_pk_bf16_f32 v234, v228, v229
	v_cvt_pk_bf16_f32 v235, v230, v231
	s_nop 1
	v_mfma_f32_32x32x16_bf16 v[16:31], v[232:235], v[108:111], v[16:31]
	v_mfma_f32_32x32x16_bf16 v[32:47], v[232:235], v[112:115], v[32:47]
	v_add_u32_e32 v221, v204, v208
	v_add_u32_e32 v222, v220, v219
	ds_read_b128 v[104:107], v221
	ds_read_b128 v[108:111], v222
	ds_read_b128 v[112:115], v222 offset:4096
	s_waitcnt vmcnt(2) lgkmcnt(3)
	v_lshlrev_b32_e32 v224, 16, v88
	v_and_b32_e32 v225, 0xffff0000, v88
	v_lshlrev_b32_e32 v226, 16, v89
	v_and_b32_e32 v227, 0xffff0000, v89
	v_lshlrev_b32_e32 v228, 16, v90
	v_and_b32_e32 v229, 0xffff0000, v90
	v_lshlrev_b32_e32 v230, 16, v91
	v_and_b32_e32 v231, 0xffff0000, v91
	v_pk_add_f32 v[224:225], v[224:225], v[64:65]
	v_pk_add_f32 v[226:227], v[226:227], v[66:67]
	v_pk_add_f32 v[228:229], v[228:229], v[68:69]
	v_pk_add_f32 v[230:231], v[230:231], v[70:71]
	v_cvt_pk_bf16_f32 v232, v224, v225
	v_cvt_pk_bf16_f32 v233, v226, v227
	v_cvt_pk_bf16_f32 v234, v228, v229
	v_cvt_pk_bf16_f32 v235, v230, v231
	s_nop 1
	v_mfma_f32_32x32x16_bf16 v[16:31], v[232:235], v[92:95], v[16:31]
	v_mfma_f32_32x32x16_bf16 v[32:47], v[232:235], v[100:103], v[32:47]
	s_waitcnt vmcnt(0) lgkmcnt(0)
	v_lshlrev_b32_e32 v224, 16, v104
	v_and_b32_e32 v225, 0xffff0000, v104
	v_lshlrev_b32_e32 v226, 16, v105
	v_and_b32_e32 v227, 0xffff0000, v105
	v_lshlrev_b32_e32 v228, 16, v106
	v_and_b32_e32 v229, 0xffff0000, v106
	v_lshlrev_b32_e32 v230, 16, v107
	v_and_b32_e32 v231, 0xffff0000, v107
	v_pk_add_f32 v[224:225], v[224:225], v[72:73]
	v_pk_add_f32 v[226:227], v[226:227], v[74:75]
	v_pk_add_f32 v[228:229], v[228:229], v[76:77]
	v_pk_add_f32 v[230:231], v[230:231], v[78:79]
	v_cvt_pk_bf16_f32 v232, v224, v225
	v_cvt_pk_bf16_f32 v233, v226, v227
	v_cvt_pk_bf16_f32 v234, v228, v229
	v_cvt_pk_bf16_f32 v235, v230, v231
	s_nop 1
	v_mfma_f32_32x32x16_bf16 v[16:31], v[232:235], v[108:111], v[16:31]
	v_mfma_f32_32x32x16_bf16 v[32:47], v[232:235], v[112:115], v[32:47]
	s_barrier
	s_nop 7
	s_nop 7
	ds_write_b32 v7, v16 offset:0
	ds_write_b32 v7, v32 offset:128
	ds_write_b32 v7, v17 offset:260
	ds_write_b32 v7, v33 offset:388
	ds_write_b32 v7, v18 offset:520
	ds_write_b32 v7, v34 offset:648
	ds_write_b32 v7, v19 offset:780
	ds_write_b32 v7, v35 offset:908
	ds_write_b32 v7, v20 offset:2080
	ds_write_b32 v7, v36 offset:2208
	ds_write_b32 v7, v21 offset:2340
	ds_write_b32 v7, v37 offset:2468
	ds_write_b32 v7, v22 offset:2600
	ds_write_b32 v7, v38 offset:2728
	ds_write_b32 v7, v23 offset:2860
	ds_write_b32 v7, v39 offset:2988
	ds_write_b32 v7, v24 offset:4160
	ds_write_b32 v7, v40 offset:4288
	ds_write_b32 v7, v25 offset:4420
	ds_write_b32 v7, v41 offset:4548
	ds_write_b32 v7, v26 offset:4680
	ds_write_b32 v7, v42 offset:4808
	ds_write_b32 v7, v27 offset:4940
	ds_write_b32 v7, v43 offset:5068
	ds_write_b32 v7, v28 offset:6240
	ds_write_b32 v7, v44 offset:6368
	ds_write_b32 v7, v29 offset:6500
	ds_write_b32 v7, v45 offset:6628
	ds_write_b32 v7, v30 offset:6760
	ds_write_b32 v7, v46 offset:6888
	ds_write_b32 v7, v31 offset:7020
	ds_write_b32 v7, v47 offset:7148
	s_waitcnt lgkmcnt(0)
	s_barrier
; DI float gelu_exact(float x) { return 0.5f * x * (1.f + erff(x * 0.7071067811865476f)); }
; DI void phase_compress(const Params& p, char* smem) {
;     ...
;     const int row = tid >> 3, c0 = (tid & 7) * 8;
; #pragma unroll
;     for (int c = 0; c < 8; ++c) {
;       float h = Hs[row * 65 + c0 + c] + Hs[(32 + row) * 65 + c0 + c] + Hs[(64 + row) * 65 + c0 + c] + Hs[(96 + row) * 65 + c0 + c];
;       Hs[row * 65 + c0 + c] = gelu_exact(h);
;     }
	v_lshrrev_b32_e32 v237, 4, v211
	v_and_b32_e32 v238, 15, v211
	v_lshlrev_b32_e32 v238, 2, v238
	v_mul_u32_u24_e32 v239, 65, v237
	v_add_lshl_u32 v240, v239, v238, 2
	v_add_u32_e32 v246, 133440, v240
	v_add_u32_e32 v240, 64, v240
	ds_read_b32 v52, v240 offset:0
	ds_read_b32 v53, v240 offset:4
	ds_read_b32 v54, v240 offset:8
	ds_read_b32 v55, v240 offset:12
	ds_read_b32 v56, v240 offset:8320
	ds_read_b32 v57, v240 offset:8324
	ds_read_b32 v58, v240 offset:8328
	ds_read_b32 v59, v240 offset:8332
	s_waitcnt lgkmcnt(0)
	ds_read_b32 v60, v240 offset:16640
	ds_read_b32 v61, v240 offset:16644
	ds_read_b32 v62, v240 offset:16648
	ds_read_b32 v63, v240 offset:16652
	ds_read_b32 v64, v240 offset:24960
	ds_read_b32 v65, v240 offset:24964
	ds_read_b32 v66, v240 offset:24968
	ds_read_b32 v67, v240 offset:24972
	s_waitcnt lgkmcnt(0)
	ds_read_b32 v68, v240 offset:33280
	ds_read_b32 v69, v240 offset:33284
	ds_read_b32 v70, v240 offset:33288
	ds_read_b32 v71, v240 offset:33292
	ds_read_b32 v72, v240 offset:41600
	ds_read_b32 v73, v240 offset:41604
	ds_read_b32 v74, v240 offset:41608
	ds_read_b32 v75, v240 offset:41612
	s_waitcnt lgkmcnt(0)
	ds_read_b32 v76, v240 offset:49920
	ds_read_b32 v77, v240 offset:49924
	ds_read_b32 v78, v240 offset:49928
	ds_read_b32 v79, v240 offset:49932
	ds_read_b32 v80, v240 offset:58240
	ds_read_b32 v81, v240 offset:58244
	ds_read_b32 v82, v240 offset:58248
	ds_read_b32 v83, v240 offset:58252
	s_waitcnt lgkmcnt(0)
	v_add_f32_e32 v48, v52, v56
	v_add_f32_e32 v49, v53, v57
	v_add_f32_e32 v50, v54, v58
	v_add_f32_e32 v51, v55, v59
	v_add_f32_e32 v48, v48, v60
	v_add_f32_e32 v49, v49, v61
	v_add_f32_e32 v50, v50, v62
	v_add_f32_e32 v51, v51, v63
	v_add_f32_e32 v48, v48, v64
	v_add_f32_e32 v49, v49, v65
	v_add_f32_e32 v50, v50, v66
	v_add_f32_e32 v51, v51, v67
	v_add_f32_e32 v48, v48, v68
	v_add_f32_e32 v49, v49, v69
	v_add_f32_e32 v50, v50, v70
	v_add_f32_e32 v51, v51, v71
	v_add_f32_e32 v48, v48, v72
	v_add_f32_e32 v49, v49, v73
	v_add_f32_e32 v50, v50, v74
	v_add_f32_e32 v51, v51, v75
	v_add_f32_e32 v48, v48, v76
	v_add_f32_e32 v49, v49, v77
	v_add_f32_e32 v50, v50, v78
	v_add_f32_e32 v51, v51, v79
	v_add_f32_e32 v48, v48, v80
	v_add_f32_e32 v49, v49, v81
	v_add_f32_e32 v50, v50, v82
	v_add_f32_e32 v51, v51, v83
	v_mul_f32_e32 v8, 0x3f3504f3, v48
	v_mov_b32_e32 v9, 0xb9c68948
	v_fma_f32 v9, |v8|, s20, v9
	v_fma_f32 v9, |v8|, v9, s21
	v_fma_f32 v9, |v8|, v9, s22
	v_fma_f32 v9, |v8|, v9, s23
	v_fma_f32 v9, |v8|, v9, s24
	v_fma_f32 v9, |v8|, v9, s25
	v_fma_f32 v9, |v8|, v9, |v8|
	v_mul_f32_e32 v10, 0xbfb8aa3b, v9
	v_fma_f32 v11, v9, s26, -v10
	v_rndne_f32_e32 v12, v10
	v_fmac_f32_e32 v11, 0xb2a5705f, v9
	v_sub_f32_e32 v10, v10, v12
	v_add_f32_e32 v10, v10, v11
	v_cvt_i32_f32_e32 v11, v12
	v_exp_f32_e32 v10, v10
	v_cmp_nlt_f32_e32 vcc, s27, v9
	v_ldexp_f32 v10, v10, v11
	s_nop 0
	v_cndmask_b32_e32 v10, 0, v10, vcc
	v_cmp_ngt_f32_e32 vcc, s28, v9
	v_mov_b32_e32 v11, 0x7f800000
	s_nop 0
	v_cndmask_b32_e32 v10, v11, v10, vcc
	v_sub_f32_e32 v10, 1.0, v10
	v_mul_f32_e32 v11, v8, v8
	v_mov_b32_e32 v12, 0x3ba10414
	v_fmamk_f32 v12, v11, 0xba1345e1, v12
	v_fmaak_f32 v12, v11, v12, 0xbcdac9b8
	v_fmaak_f32 v12, v11, v12, 0x3de703be
	v_fmaak_f32 v12, v11, v12, 0xbec09330
	v_fmaak_f32 v12, v11, v12, 0x3e0375d0
	v_fma_f32 v12, |v8|, v12, |v8|
	v_cmp_nlt_f32_e64 vcc, |v8|, 1.0
	s_nop 1
	v_cndmask_b32_e32 v10, v12, v10, vcc
	v_bfi_b32 v10, s29, v10, v8
	v_mul_f32_e32 v48, 0.5, v48
	v_add_f32_e32 v10, 1.0, v10
	v_mul_f32_e32 v48, v48, v10
	v_mul_f32_e32 v8, 0x3f3504f3, v49
	v_mov_b32_e32 v9, 0xb9c68948
	v_fma_f32 v9, |v8|, s20, v9
	v_fma_f32 v9, |v8|, v9, s21
	v_fma_f32 v9, |v8|, v9, s22
	v_fma_f32 v9, |v8|, v9, s23
	v_fma_f32 v9, |v8|, v9, s24
	v_fma_f32 v9, |v8|, v9, s25
	v_fma_f32 v9, |v8|, v9, |v8|
	v_mul_f32_e32 v10, 0xbfb8aa3b, v9
	v_fma_f32 v11, v9, s26, -v10
	v_rndne_f32_e32 v12, v10
	v_fmac_f32_e32 v11, 0xb2a5705f, v9
	v_sub_f32_e32 v10, v10, v12
	v_add_f32_e32 v10, v10, v11
	v_cvt_i32_f32_e32 v11, v12
	v_exp_f32_e32 v10, v10
	v_cmp_nlt_f32_e32 vcc, s27, v9
	v_ldexp_f32 v10, v10, v11
	s_nop 0
	v_cndmask_b32_e32 v10, 0, v10, vcc
	v_cmp_ngt_f32_e32 vcc, s28, v9
	v_mov_b32_e32 v11, 0x7f800000
	s_nop 0
	v_cndmask_b32_e32 v10, v11, v10, vcc
	v_sub_f32_e32 v10, 1.0, v10
	v_mul_f32_e32 v11, v8, v8
	v_mov_b32_e32 v12, 0x3ba10414
	v_fmamk_f32 v12, v11, 0xba1345e1, v12
	v_fmaak_f32 v12, v11, v12, 0xbcdac9b8
	v_fmaak_f32 v12, v11, v12, 0x3de703be
	v_fmaak_f32 v12, v11, v12, 0xbec09330
	v_fmaak_f32 v12, v11, v12, 0x3e0375d0
	v_fma_f32 v12, |v8|, v12, |v8|
	v_cmp_nlt_f32_e64 vcc, |v8|, 1.0
	s_nop 1
	v_cndmask_b32_e32 v10, v12, v10, vcc
	v_bfi_b32 v10, s29, v10, v8
	v_mul_f32_e32 v49, 0.5, v49
	v_add_f32_e32 v10, 1.0, v10
	v_mul_f32_e32 v49, v49, v10
	v_mul_f32_e32 v8, 0x3f3504f3, v50
	v_mov_b32_e32 v9, 0xb9c68948
	v_fma_f32 v9, |v8|, s20, v9
	v_fma_f32 v9, |v8|, v9, s21
	v_fma_f32 v9, |v8|, v9, s22
	v_fma_f32 v9, |v8|, v9, s23
	v_fma_f32 v9, |v8|, v9, s24
	v_fma_f32 v9, |v8|, v9, s25
	v_fma_f32 v9, |v8|, v9, |v8|
	v_mul_f32_e32 v10, 0xbfb8aa3b, v9
	v_fma_f32 v11, v9, s26, -v10
	v_rndne_f32_e32 v12, v10
	v_fmac_f32_e32 v11, 0xb2a5705f, v9
	v_sub_f32_e32 v10, v10, v12
	v_add_f32_e32 v10, v10, v11
	v_cvt_i32_f32_e32 v11, v12
	v_exp_f32_e32 v10, v10
	v_cmp_nlt_f32_e32 vcc, s27, v9
	v_ldexp_f32 v10, v10, v11
	s_nop 0
	v_cndmask_b32_e32 v10, 0, v10, vcc
	v_cmp_ngt_f32_e32 vcc, s28, v9
	v_mov_b32_e32 v11, 0x7f800000
	s_nop 0
	v_cndmask_b32_e32 v10, v11, v10, vcc
	v_sub_f32_e32 v10, 1.0, v10
	v_mul_f32_e32 v11, v8, v8
	v_mov_b32_e32 v12, 0x3ba10414
	v_fmamk_f32 v12, v11, 0xba1345e1, v12
	v_fmaak_f32 v12, v11, v12, 0xbcdac9b8
	v_fmaak_f32 v12, v11, v12, 0x3de703be
; DI void hsync() { hsync_impl(false); }
; DI float gelu_exact(float x) { return 0.5f * x * (1.f + erff(x * 0.7071067811865476f)); }
; DI void phase_compress(const Params& p, char* smem) {
;     ...
;       float h = Hs[row * 65 + c0 + c] + Hs[(32 + row) * 65 + c0 + c] + Hs[(64 + row) * 65 + c0 + c] + Hs[(96 + row) * 65 + c0 + c];
;       Hs[row * 65 + c0 + c] = gelu_exact(h);
;     }
;     hsync();
;     {
;       const float* w2 = kv ? p.w_v2 : p.w_k2;
;       float o[8];
; #pragma unroll
;       for (int c = 0; c < 8; ++c) o[c] = 0.f;
; #pragma unroll 8
;       for (int i = 0; i < 64; ++i) {
;         float hv = Hs[row * 65 + i];
;         float4 wa = *(const float4*)(w2 + i * 64 + c0);
;         float4 wb = *(const float4*)(w2 + i * 64 + c0 + 4);
;         o[0] += hv * wa.x; o[1] += hv * wa.y; o[2] += hv * wa.z; o[3] += hv * wa.w;
;         o[4] += hv * wb.x; o[5] += hv * wb.y; o[6] += hv * wb.z; o[7] += hv * wb.w;
;       }
	v_fmaak_f32 v12, v11, v12, 0xbec09330
	v_fmaak_f32 v12, v11, v12, 0x3e0375d0
	v_fma_f32 v12, |v8|, v12, |v8|
	v_cmp_nlt_f32_e64 vcc, |v8|, 1.0
	s_nop 1
	v_cndmask_b32_e32 v10, v12, v10, vcc
	v_bfi_b32 v10, s29, v10, v8
	v_mul_f32_e32 v50, 0.5, v50
	v_add_f32_e32 v10, 1.0, v10
	v_mul_f32_e32 v50, v50, v10
	v_mul_f32_e32 v8, 0x3f3504f3, v51
	v_mov_b32_e32 v9, 0xb9c68948
	v_fma_f32 v9, |v8|, s20, v9
	v_fma_f32 v9, |v8|, v9, s21
	v_fma_f32 v9, |v8|, v9, s22
	v_fma_f32 v9, |v8|, v9, s23
	v_fma_f32 v9, |v8|, v9, s24
	v_fma_f32 v9, |v8|, v9, s25
	v_fma_f32 v9, |v8|, v9, |v8|
	v_mul_f32_e32 v10, 0xbfb8aa3b, v9
	v_fma_f32 v11, v9, s26, -v10
	v_rndne_f32_e32 v12, v10
	v_fmac_f32_e32 v11, 0xb2a5705f, v9
	v_sub_f32_e32 v10, v10, v12
	v_add_f32_e32 v10, v10, v11
	v_cvt_i32_f32_e32 v11, v12
	v_exp_f32_e32 v10, v10
	v_cmp_nlt_f32_e32 vcc, s27, v9
	v_ldexp_f32 v10, v10, v11
	s_nop 0
	v_cndmask_b32_e32 v10, 0, v10, vcc
	v_cmp_ngt_f32_e32 vcc, s28, v9
	v_mov_b32_e32 v11, 0x7f800000
	s_nop 0
	v_cndmask_b32_e32 v10, v11, v10, vcc
	v_sub_f32_e32 v10, 1.0, v10
	v_mul_f32_e32 v11, v8, v8
	v_mov_b32_e32 v12, 0x3ba10414
	v_fmamk_f32 v12, v11, 0xba1345e1, v12
	v_fmaak_f32 v12, v11, v12, 0xbcdac9b8
	v_fmaak_f32 v12, v11, v12, 0x3de703be
	v_fmaak_f32 v12, v11, v12, 0xbec09330
	v_fmaak_f32 v12, v11, v12, 0x3e0375d0
	v_fma_f32 v12, |v8|, v12, |v8|
	v_cmp_nlt_f32_e64 vcc, |v8|, 1.0
	s_nop 1
	v_cndmask_b32_e32 v10, v12, v10, vcc
	v_bfi_b32 v10, s29, v10, v8
	v_mul_f32_e32 v51, 0.5, v51
	v_add_f32_e32 v10, 1.0, v10
	v_mul_f32_e32 v51, v51, v10
	ds_write_b32 v246, v48 offset:0
	ds_write_b32 v246, v49 offset:4
	ds_write_b32 v246, v50 offset:8
	ds_write_b32 v246, v51 offset:12
	s_waitcnt lgkmcnt(0)
	s_barrier
	v_mul_u32_u24_e32 v241, 260, v237
	v_add_u32_e32 v241, 133440, v241
	v_lshlrev_b32_e32 v242, 2, v238
	v_add_u32_e32 v242, 141760, v242
	v_mov_b32_e32 v132, 0
	v_mov_b32_e32 v133, 0
	v_mov_b32_e32 v134, 0
	v_mov_b32_e32 v135, 0
	ds_read_b32 v56, v241 offset:0
	ds_read_b128 v[64:67], v242 offset:0
	ds_read_b32 v57, v241 offset:4
	ds_read_b128 v[68:71], v242 offset:256
	ds_read_b32 v58, v241 offset:8
	ds_read_b128 v[72:75], v242 offset:512
	ds_read_b32 v59, v241 offset:12
	ds_read_b128 v[76:79], v242 offset:768
	s_waitcnt lgkmcnt(6)
	v_fmac_f32_e32 v132, v56, v64
	v_fmac_f32_e32 v133, v56, v65
	v_fmac_f32_e32 v134, v56, v66
	v_fmac_f32_e32 v135, v56, v67
	s_waitcnt lgkmcnt(4)
	v_fmac_f32_e32 v132, v57, v68
	v_fmac_f32_e32 v133, v57, v69
	v_fmac_f32_e32 v134, v57, v70
	v_fmac_f32_e32 v135, v57, v71
	s_waitcnt lgkmcnt(2)
	v_fmac_f32_e32 v132, v58, v72
	v_fmac_f32_e32 v133, v58, v73
	v_fmac_f32_e32 v134, v58, v74
	v_fmac_f32_e32 v135, v58, v75
	s_waitcnt lgkmcnt(0)
	v_fmac_f32_e32 v132, v59, v76
	v_fmac_f32_e32 v133, v59, v77
	v_fmac_f32_e32 v134, v59, v78
	v_fmac_f32_e32 v135, v59, v79
	ds_read_b32 v56, v241 offset:16
	ds_read_b128 v[64:67], v242 offset:1024
	ds_read_b32 v57, v241 offset:20
	ds_read_b128 v[68:71], v242 offset:1280
	ds_read_b32 v58, v241 offset:24
	ds_read_b128 v[72:75], v242 offset:1536
	ds_read_b32 v59, v241 offset:28
	ds_read_b128 v[76:79], v242 offset:1792
	s_waitcnt lgkmcnt(6)
	v_fmac_f32_e32 v132, v56, v64
	v_fmac_f32_e32 v133, v56, v65
	v_fmac_f32_e32 v134, v56, v66
	v_fmac_f32_e32 v135, v56, v67
	s_waitcnt lgkmcnt(4)
	v_fmac_f32_e32 v132, v57, v68
	v_fmac_f32_e32 v133, v57, v69
	v_fmac_f32_e32 v134, v57, v70
	v_fmac_f32_e32 v135, v57, v71
	s_waitcnt lgkmcnt(2)
	v_fmac_f32_e32 v132, v58, v72
	v_fmac_f32_e32 v133, v58, v73
	v_fmac_f32_e32 v134, v58, v74
	v_fmac_f32_e32 v135, v58, v75
	s_waitcnt lgkmcnt(0)
	v_fmac_f32_e32 v132, v59, v76
	v_fmac_f32_e32 v133, v59, v77
	v_fmac_f32_e32 v134, v59, v78
	v_fmac_f32_e32 v135, v59, v79
	ds_read_b32 v56, v241 offset:32
	ds_read_b128 v[64:67], v242 offset:2048
	ds_read_b32 v57, v241 offset:36
	ds_read_b128 v[68:71], v242 offset:2304
	ds_read_b32 v58, v241 offset:40
	ds_read_b128 v[72:75], v242 offset:2560
	ds_read_b32 v59, v241 offset:44
	ds_read_b128 v[76:79], v242 offset:2816
	s_waitcnt lgkmcnt(6)
	v_fmac_f32_e32 v132, v56, v64
	v_fmac_f32_e32 v133, v56, v65
	v_fmac_f32_e32 v134, v56, v66
	v_fmac_f32_e32 v135, v56, v67
	s_waitcnt lgkmcnt(4)
	v_fmac_f32_e32 v132, v57, v68
	v_fmac_f32_e32 v133, v57, v69
	v_fmac_f32_e32 v134, v57, v70
	v_fmac_f32_e32 v135, v57, v71
	s_waitcnt lgkmcnt(2)
	v_fmac_f32_e32 v132, v58, v72
	v_fmac_f32_e32 v133, v58, v73
	v_fmac_f32_e32 v134, v58, v74
	v_fmac_f32_e32 v135, v58, v75
	s_waitcnt lgkmcnt(0)
	v_fmac_f32_e32 v132, v59, v76
	v_fmac_f32_e32 v133, v59, v77
	v_fmac_f32_e32 v134, v59, v78
	v_fmac_f32_e32 v135, v59, v79
	ds_read_b32 v56, v241 offset:48
	ds_read_b128 v[64:67], v242 offset:3072
	ds_read_b32 v57, v241 offset:52
	ds_read_b128 v[68:71], v242 offset:3328
	ds_read_b32 v58, v241 offset:56
	ds_read_b128 v[72:75], v242 offset:3584
	ds_read_b32 v59, v241 offset:60
	ds_read_b128 v[76:79], v242 offset:3840
	s_waitcnt lgkmcnt(6)
	v_fmac_f32_e32 v132, v56, v64
	v_fmac_f32_e32 v133, v56, v65
	v_fmac_f32_e32 v134, v56, v66
	v_fmac_f32_e32 v135, v56, v67
	s_waitcnt lgkmcnt(4)
	v_fmac_f32_e32 v132, v57, v68
	v_fmac_f32_e32 v133, v57, v69
	v_fmac_f32_e32 v134, v57, v70
	v_fmac_f32_e32 v135, v57, v71
	s_waitcnt lgkmcnt(2)
	v_fmac_f32_e32 v132, v58, v72
	v_fmac_f32_e32 v133, v58, v73
	v_fmac_f32_e32 v134, v58, v74
	v_fmac_f32_e32 v135, v58, v75
	s_waitcnt lgkmcnt(0)
	v_fmac_f32_e32 v132, v59, v76
	v_fmac_f32_e32 v133, v59, v77
	v_fmac_f32_e32 v134, v59, v78
	v_fmac_f32_e32 v135, v59, v79
	ds_read_b32 v56, v241 offset:64
	ds_read_b128 v[64:67], v242 offset:4096
	ds_read_b32 v57, v241 offset:68
	ds_read_b128 v[68:71], v242 offset:4352
	ds_read_b32 v58, v241 offset:72
	ds_read_b128 v[72:75], v242 offset:4608
	ds_read_b32 v59, v241 offset:76
	ds_read_b128 v[76:79], v242 offset:4864
	s_waitcnt lgkmcnt(6)
; DI void phase_compress(const Params& p, char* smem) {
;     ...
; #pragma unroll 8
;       for (int i = 0; i < 64; ++i) {
;         float hv = Hs[row * 65 + i];
;         float4 wa = *(const float4*)(w2 + i * 64 + c0);
;         float4 wb = *(const float4*)(w2 + i * 64 + c0 + 4);
;         o[0] += hv * wa.x; o[1] += hv * wa.y; o[2] += hv * wa.z; o[3] += hv * wa.w;
;         o[4] += hv * wb.x; o[5] += hv * wb.y; o[6] += hv * wb.z; o[7] += hv * wb.w;
;       }
	v_fmac_f32_e32 v132, v56, v64
	v_fmac_f32_e32 v133, v56, v65
	v_fmac_f32_e32 v134, v56, v66
	v_fmac_f32_e32 v135, v56, v67
	s_waitcnt lgkmcnt(4)
	v_fmac_f32_e32 v132, v57, v68
	v_fmac_f32_e32 v133, v57, v69
	v_fmac_f32_e32 v134, v57, v70
	v_fmac_f32_e32 v135, v57, v71
	s_waitcnt lgkmcnt(2)
	v_fmac_f32_e32 v132, v58, v72
	v_fmac_f32_e32 v133, v58, v73
	v_fmac_f32_e32 v134, v58, v74
	v_fmac_f32_e32 v135, v58, v75
	s_waitcnt lgkmcnt(0)
	v_fmac_f32_e32 v132, v59, v76
	v_fmac_f32_e32 v133, v59, v77
	v_fmac_f32_e32 v134, v59, v78
	v_fmac_f32_e32 v135, v59, v79
	ds_read_b32 v56, v241 offset:80
	ds_read_b128 v[64:67], v242 offset:5120
	ds_read_b32 v57, v241 offset:84
	ds_read_b128 v[68:71], v242 offset:5376
	ds_read_b32 v58, v241 offset:88
	ds_read_b128 v[72:75], v242 offset:5632
	ds_read_b32 v59, v241 offset:92
	ds_read_b128 v[76:79], v242 offset:5888
	s_waitcnt lgkmcnt(6)
	v_fmac_f32_e32 v132, v56, v64
	v_fmac_f32_e32 v133, v56, v65
	v_fmac_f32_e32 v134, v56, v66
	v_fmac_f32_e32 v135, v56, v67
	s_waitcnt lgkmcnt(4)
	v_fmac_f32_e32 v132, v57, v68
	v_fmac_f32_e32 v133, v57, v69
	v_fmac_f32_e32 v134, v57, v70
	v_fmac_f32_e32 v135, v57, v71
	s_waitcnt lgkmcnt(2)
	v_fmac_f32_e32 v132, v58, v72
	v_fmac_f32_e32 v133, v58, v73
	v_fmac_f32_e32 v134, v58, v74
	v_fmac_f32_e32 v135, v58, v75
	s_waitcnt lgkmcnt(0)
	v_fmac_f32_e32 v132, v59, v76
	v_fmac_f32_e32 v133, v59, v77
	v_fmac_f32_e32 v134, v59, v78
	v_fmac_f32_e32 v135, v59, v79
	ds_read_b32 v56, v241 offset:96
	ds_read_b128 v[64:67], v242 offset:6144
	ds_read_b32 v57, v241 offset:100
	ds_read_b128 v[68:71], v242 offset:6400
	ds_read_b32 v58, v241 offset:104
	ds_read_b128 v[72:75], v242 offset:6656
	ds_read_b32 v59, v241 offset:108
	ds_read_b128 v[76:79], v242 offset:6912
	s_waitcnt lgkmcnt(6)
	v_fmac_f32_e32 v132, v56, v64
	v_fmac_f32_e32 v133, v56, v65
	v_fmac_f32_e32 v134, v56, v66
	v_fmac_f32_e32 v135, v56, v67
	s_waitcnt lgkmcnt(4)
	v_fmac_f32_e32 v132, v57, v68
	v_fmac_f32_e32 v133, v57, v69
	v_fmac_f32_e32 v134, v57, v70
	v_fmac_f32_e32 v135, v57, v71
	s_waitcnt lgkmcnt(2)
	v_fmac_f32_e32 v132, v58, v72
	v_fmac_f32_e32 v133, v58, v73
	v_fmac_f32_e32 v134, v58, v74
	v_fmac_f32_e32 v135, v58, v75
	s_waitcnt lgkmcnt(0)
	v_fmac_f32_e32 v132, v59, v76
	v_fmac_f32_e32 v133, v59, v77
	v_fmac_f32_e32 v134, v59, v78
	v_fmac_f32_e32 v135, v59, v79
	ds_read_b32 v56, v241 offset:112
	ds_read_b128 v[64:67], v242 offset:7168
	ds_read_b32 v57, v241 offset:116
	ds_read_b128 v[68:71], v242 offset:7424
	ds_read_b32 v58, v241 offset:120
	ds_read_b128 v[72:75], v242 offset:7680
	ds_read_b32 v59, v241 offset:124
	ds_read_b128 v[76:79], v242 offset:7936
	s_waitcnt lgkmcnt(6)
	v_fmac_f32_e32 v132, v56, v64
	v_fmac_f32_e32 v133, v56, v65
	v_fmac_f32_e32 v134, v56, v66
	v_fmac_f32_e32 v135, v56, v67
	s_waitcnt lgkmcnt(4)
	v_fmac_f32_e32 v132, v57, v68
	v_fmac_f32_e32 v133, v57, v69
	v_fmac_f32_e32 v134, v57, v70
	v_fmac_f32_e32 v135, v57, v71
	s_waitcnt lgkmcnt(2)
	v_fmac_f32_e32 v132, v58, v72
	v_fmac_f32_e32 v133, v58, v73
	v_fmac_f32_e32 v134, v58, v74
	v_fmac_f32_e32 v135, v58, v75
	s_waitcnt lgkmcnt(0)
	v_fmac_f32_e32 v132, v59, v76
	v_fmac_f32_e32 v133, v59, v77
	v_fmac_f32_e32 v134, v59, v78
	v_fmac_f32_e32 v135, v59, v79
	ds_read_b32 v56, v241 offset:128
	ds_read_b128 v[64:67], v242 offset:8192
	ds_read_b32 v57, v241 offset:132
	ds_read_b128 v[68:71], v242 offset:8448
	ds_read_b32 v58, v241 offset:136
	ds_read_b128 v[72:75], v242 offset:8704
	ds_read_b32 v59, v241 offset:140
	ds_read_b128 v[76:79], v242 offset:8960
	s_waitcnt lgkmcnt(6)
	v_fmac_f32_e32 v132, v56, v64
	v_fmac_f32_e32 v133, v56, v65
	v_fmac_f32_e32 v134, v56, v66
	v_fmac_f32_e32 v135, v56, v67
	s_waitcnt lgkmcnt(4)
	v_fmac_f32_e32 v132, v57, v68
	v_fmac_f32_e32 v133, v57, v69
	v_fmac_f32_e32 v134, v57, v70
	v_fmac_f32_e32 v135, v57, v71
	s_waitcnt lgkmcnt(2)
	v_fmac_f32_e32 v132, v58, v72
	v_fmac_f32_e32 v133, v58, v73
	v_fmac_f32_e32 v134, v58, v74
	v_fmac_f32_e32 v135, v58, v75
	s_waitcnt lgkmcnt(0)
	v_fmac_f32_e32 v132, v59, v76
	v_fmac_f32_e32 v133, v59, v77
	v_fmac_f32_e32 v134, v59, v78
	v_fmac_f32_e32 v135, v59, v79
	ds_read_b32 v56, v241 offset:144
	ds_read_b128 v[64:67], v242 offset:9216
	ds_read_b32 v57, v241 offset:148
	ds_read_b128 v[68:71], v242 offset:9472
	ds_read_b32 v58, v241 offset:152
	ds_read_b128 v[72:75], v242 offset:9728
	ds_read_b32 v59, v241 offset:156
	ds_read_b128 v[76:79], v242 offset:9984
	s_waitcnt lgkmcnt(6)
	v_fmac_f32_e32 v132, v56, v64
	v_fmac_f32_e32 v133, v56, v65
	v_fmac_f32_e32 v134, v56, v66
	v_fmac_f32_e32 v135, v56, v67
	s_waitcnt lgkmcnt(4)
	v_fmac_f32_e32 v132, v57, v68
	v_fmac_f32_e32 v133, v57, v69
	v_fmac_f32_e32 v134, v57, v70
	v_fmac_f32_e32 v135, v57, v71
	s_waitcnt lgkmcnt(2)
	v_fmac_f32_e32 v132, v58, v72
	v_fmac_f32_e32 v133, v58, v73
	v_fmac_f32_e32 v134, v58, v74
	v_fmac_f32_e32 v135, v58, v75
	s_waitcnt lgkmcnt(0)
	v_fmac_f32_e32 v132, v59, v76
	v_fmac_f32_e32 v133, v59, v77
	v_fmac_f32_e32 v134, v59, v78
	v_fmac_f32_e32 v135, v59, v79
	ds_read_b32 v56, v241 offset:160
	ds_read_b128 v[64:67], v242 offset:10240
	ds_read_b32 v57, v241 offset:164
	ds_read_b128 v[68:71], v242 offset:10496
	ds_read_b32 v58, v241 offset:168
	ds_read_b128 v[72:75], v242 offset:10752
	ds_read_b32 v59, v241 offset:172
	ds_read_b128 v[76:79], v242 offset:11008
	s_waitcnt lgkmcnt(6)
	v_fmac_f32_e32 v132, v56, v64
	v_fmac_f32_e32 v133, v56, v65
	v_fmac_f32_e32 v134, v56, v66
	v_fmac_f32_e32 v135, v56, v67
	s_waitcnt lgkmcnt(4)
	v_fmac_f32_e32 v132, v57, v68
	v_fmac_f32_e32 v133, v57, v69
	v_fmac_f32_e32 v134, v57, v70
	v_fmac_f32_e32 v135, v57, v71
	s_waitcnt lgkmcnt(2)
; DI void phase_compress(const Params& p, char* smem) {
;     ...
;     {
;       const float* w2 = kv ? p.w_v2 : p.w_k2;
;       float o[8];
; #pragma unroll
;       for (int c = 0; c < 8; ++c) o[c] = 0.f;
; #pragma unroll 8
;       for (int i = 0; i < 64; ++i) {
;         float hv = Hs[row * 65 + i];
;         float4 wa = *(const float4*)(w2 + i * 64 + c0);
;         float4 wb = *(const float4*)(w2 + i * 64 + c0 + 4);
;         o[0] += hv * wa.x; o[1] += hv * wa.y; o[2] += hv * wa.z; o[3] += hv * wa.w;
;         o[4] += hv * wb.x; o[5] += hv * wb.y; o[6] += hv * wb.z; o[7] += hv * wb.w;
;       }
;       int mi2 = mt * 32 + row;
;       int bg2 = mi2 >> 8, n2 = mi2 & 255;
;       if (n2 == 255) {
; #pragma unroll
;         for (int c = 0; c < 8; ++c) o[c] = 0.f;
;       }
;       if (kv == 0) {
;         u32x4 w;
;         w[0] = pack2(o[0], o[1]); w[1] = pack2(o[2], o[3]); w[2] = pack2(o[4], o[5]); w[3] = pack2(o[6], o[7]);
;         *(u32x4*)(KCMP + ((size_t)(bg2 * 256 + n2)) * 64 + c0) = w;
	v_fmac_f32_e32 v132, v58, v72
	v_fmac_f32_e32 v133, v58, v73
	v_fmac_f32_e32 v134, v58, v74
	v_fmac_f32_e32 v135, v58, v75
	s_waitcnt lgkmcnt(0)
	v_fmac_f32_e32 v132, v59, v76
	v_fmac_f32_e32 v133, v59, v77
	v_fmac_f32_e32 v134, v59, v78
	v_fmac_f32_e32 v135, v59, v79
	ds_read_b32 v56, v241 offset:176
	ds_read_b128 v[64:67], v242 offset:11264
	ds_read_b32 v57, v241 offset:180
	ds_read_b128 v[68:71], v242 offset:11520
	ds_read_b32 v58, v241 offset:184
	ds_read_b128 v[72:75], v242 offset:11776
	ds_read_b32 v59, v241 offset:188
	ds_read_b128 v[76:79], v242 offset:12032
	s_waitcnt lgkmcnt(6)
	v_fmac_f32_e32 v132, v56, v64
	v_fmac_f32_e32 v133, v56, v65
	v_fmac_f32_e32 v134, v56, v66
	v_fmac_f32_e32 v135, v56, v67
	s_waitcnt lgkmcnt(4)
	v_fmac_f32_e32 v132, v57, v68
	v_fmac_f32_e32 v133, v57, v69
	v_fmac_f32_e32 v134, v57, v70
	v_fmac_f32_e32 v135, v57, v71
	s_waitcnt lgkmcnt(2)
	v_fmac_f32_e32 v132, v58, v72
	v_fmac_f32_e32 v133, v58, v73
	v_fmac_f32_e32 v134, v58, v74
	v_fmac_f32_e32 v135, v58, v75
	s_waitcnt lgkmcnt(0)
	v_fmac_f32_e32 v132, v59, v76
	v_fmac_f32_e32 v133, v59, v77
	v_fmac_f32_e32 v134, v59, v78
	v_fmac_f32_e32 v135, v59, v79
	ds_read_b32 v56, v241 offset:192
	ds_read_b128 v[64:67], v242 offset:12288
	ds_read_b32 v57, v241 offset:196
	ds_read_b128 v[68:71], v242 offset:12544
	ds_read_b32 v58, v241 offset:200
	ds_read_b128 v[72:75], v242 offset:12800
	ds_read_b32 v59, v241 offset:204
	ds_read_b128 v[76:79], v242 offset:13056
	s_waitcnt lgkmcnt(6)
	v_fmac_f32_e32 v132, v56, v64
	v_fmac_f32_e32 v133, v56, v65
	v_fmac_f32_e32 v134, v56, v66
	v_fmac_f32_e32 v135, v56, v67
	s_waitcnt lgkmcnt(4)
	v_fmac_f32_e32 v132, v57, v68
	v_fmac_f32_e32 v133, v57, v69
	v_fmac_f32_e32 v134, v57, v70
	v_fmac_f32_e32 v135, v57, v71
	s_waitcnt lgkmcnt(2)
	v_fmac_f32_e32 v132, v58, v72
	v_fmac_f32_e32 v133, v58, v73
	v_fmac_f32_e32 v134, v58, v74
	v_fmac_f32_e32 v135, v58, v75
	s_waitcnt lgkmcnt(0)
	v_fmac_f32_e32 v132, v59, v76
	v_fmac_f32_e32 v133, v59, v77
	v_fmac_f32_e32 v134, v59, v78
	v_fmac_f32_e32 v135, v59, v79
	ds_read_b32 v56, v241 offset:208
	ds_read_b128 v[64:67], v242 offset:13312
	ds_read_b32 v57, v241 offset:212
	ds_read_b128 v[68:71], v242 offset:13568
	ds_read_b32 v58, v241 offset:216
	ds_read_b128 v[72:75], v242 offset:13824
	ds_read_b32 v59, v241 offset:220
	ds_read_b128 v[76:79], v242 offset:14080
	s_waitcnt lgkmcnt(6)
	v_fmac_f32_e32 v132, v56, v64
	v_fmac_f32_e32 v133, v56, v65
	v_fmac_f32_e32 v134, v56, v66
	v_fmac_f32_e32 v135, v56, v67
	s_waitcnt lgkmcnt(4)
	v_fmac_f32_e32 v132, v57, v68
	v_fmac_f32_e32 v133, v57, v69
	v_fmac_f32_e32 v134, v57, v70
	v_fmac_f32_e32 v135, v57, v71
	s_waitcnt lgkmcnt(2)
	v_fmac_f32_e32 v132, v58, v72
	v_fmac_f32_e32 v133, v58, v73
	v_fmac_f32_e32 v134, v58, v74
	v_fmac_f32_e32 v135, v58, v75
	s_waitcnt lgkmcnt(0)
	v_fmac_f32_e32 v132, v59, v76
	v_fmac_f32_e32 v133, v59, v77
	v_fmac_f32_e32 v134, v59, v78
	v_fmac_f32_e32 v135, v59, v79
	ds_read_b32 v56, v241 offset:224
	ds_read_b128 v[64:67], v242 offset:14336
	ds_read_b32 v57, v241 offset:228
	ds_read_b128 v[68:71], v242 offset:14592
	ds_read_b32 v58, v241 offset:232
	ds_read_b128 v[72:75], v242 offset:14848
	ds_read_b32 v59, v241 offset:236
	ds_read_b128 v[76:79], v242 offset:15104
	s_waitcnt lgkmcnt(6)
	v_fmac_f32_e32 v132, v56, v64
	v_fmac_f32_e32 v133, v56, v65
	v_fmac_f32_e32 v134, v56, v66
	v_fmac_f32_e32 v135, v56, v67
	s_waitcnt lgkmcnt(4)
	v_fmac_f32_e32 v132, v57, v68
	v_fmac_f32_e32 v133, v57, v69
	v_fmac_f32_e32 v134, v57, v70
	v_fmac_f32_e32 v135, v57, v71
	s_waitcnt lgkmcnt(2)
	v_fmac_f32_e32 v132, v58, v72
	v_fmac_f32_e32 v133, v58, v73
	v_fmac_f32_e32 v134, v58, v74
	v_fmac_f32_e32 v135, v58, v75
	s_waitcnt lgkmcnt(0)
	v_fmac_f32_e32 v132, v59, v76
	v_fmac_f32_e32 v133, v59, v77
	v_fmac_f32_e32 v134, v59, v78
	v_fmac_f32_e32 v135, v59, v79
	ds_read_b32 v56, v241 offset:240
	ds_read_b128 v[64:67], v242 offset:15360
	ds_read_b32 v57, v241 offset:244
	ds_read_b128 v[68:71], v242 offset:15616
	ds_read_b32 v58, v241 offset:248
	ds_read_b128 v[72:75], v242 offset:15872
	ds_read_b32 v59, v241 offset:252
	ds_read_b128 v[76:79], v242 offset:16128
	s_waitcnt lgkmcnt(6)
	v_fmac_f32_e32 v132, v56, v64
	v_fmac_f32_e32 v133, v56, v65
	v_fmac_f32_e32 v134, v56, v66
	v_fmac_f32_e32 v135, v56, v67
	s_waitcnt lgkmcnt(4)
	v_fmac_f32_e32 v132, v57, v68
	v_fmac_f32_e32 v133, v57, v69
	v_fmac_f32_e32 v134, v57, v70
	v_fmac_f32_e32 v135, v57, v71
	s_waitcnt lgkmcnt(2)
	v_fmac_f32_e32 v132, v58, v72
	v_fmac_f32_e32 v133, v58, v73
	v_fmac_f32_e32 v134, v58, v74
	v_fmac_f32_e32 v135, v58, v75
	s_waitcnt lgkmcnt(0)
	v_fmac_f32_e32 v132, v59, v76
	v_fmac_f32_e32 v133, v59, v77
	v_fmac_f32_e32 v134, v59, v78
	v_fmac_f32_e32 v135, v59, v79
	v_lshl_add_u32 v243, s12, 5, v237
	v_lshrrev_b32_e32 v244, 8, v243
	v_and_b32_e32 v245, 0xff, v243
	v_mov_b32_e32 v8, 0
	v_cmp_eq_u32_e32 vcc, 0xff, v245
	s_nop 1
	v_cndmask_b32_e32 v132, v132, v8, vcc
	v_cndmask_b32_e32 v133, v133, v8, vcc
	v_cndmask_b32_e32 v134, v134, v8, vcc
	v_cndmask_b32_e32 v135, v135, v8, vcc
	s_cmp_eq_u32 s11, 0
	s_cbranch_scc0 .Lcp_vout
	v_lshlrev_b32_e32 v9, 7, v243
	v_lshl_add_u32 v9, v238, 1, v9
	v_cvt_pk_bf16_f32 v10, v132, v133
	v_cvt_pk_bf16_f32 v11, v134, v135
	s_nop 0
	global_store_dwordx2 v9, v[10:11], s[8:9]
	s_branch .Lcp_done
; DI void hsync() { hsync_impl(false); }
; DI int swap23(int t) { return (t & ~12) | ((t & 4) << 1) | ((t & 8) >> 1); }
; __device__ __forceinline__ unsigned xb_add(unsigned* p, unsigned v) { return __hip_atomic_fetch_add(p, v, __ATOMIC_RELAXED, __HIP_MEMORY_SCOPE_AGENT); }
; __device__ __forceinline__ void xcd_barrier(const XcdBarrier& b) {
;     asm volatile("s_waitcnt vmcnt(0)" ::: "memory");
;     __syncthreads();
;     if (threadIdx.x == 0) {
;         unsigned* bar = b.bar;
;         __builtin_amdgcn_s_waitcnt(0);
;         unsigned nloc = b.st[0], nx = b.st[1];
;         if (nloc == 0u) { xcd_barrier_complete(bar, b.x, nloc, nx); b.st[0] = nloc; b.st[1] = nx; }
;         const unsigned old = xb_add(&bar[XB_XSUB(b.x)], 1u);
; DI void phase_compress(const Params& p, char* smem) {
;     ...
;       } else {
; #pragma unroll
;         for (int c = 0; c < 8; ++c) VCMPT[((size_t)(bg2 * 64 + c0 + c)) * 256 + swap23(n2)] = f2bf(o[c]);
;       }
;     }
;     hsync();
;   }
.Lcp_vout:
	v_and_b32_e32 v12, 0xf3, v245
	v_and_b32_e32 v13, 4, v245
	v_and_b32_e32 v14, 8, v245
	v_lshl_or_b32 v12, v13, 1, v12
	v_lshrrev_b32_e32 v14, 1, v14
	v_or_b32_e32 v12, v12, v14
	v_lshlrev_b32_e32 v9, 15, v244
	v_lshl_add_u32 v9, v238, 9, v9
	v_lshl_add_u32 v9, v12, 1, v9
	v_cvt_pk_bf16_f32 v10, v132, v132
	s_nop 0
	global_store_short v9, v10, s[8:9] offset:0
	s_nop 1
	v_cvt_pk_bf16_f32 v10, v133, v133
	s_nop 0
	global_store_short v9, v10, s[8:9] offset:512
	s_nop 1
	v_cvt_pk_bf16_f32 v10, v134, v134
	s_nop 0
	global_store_short v9, v10, s[8:9] offset:1024
	s_nop 1
	v_cvt_pk_bf16_f32 v10, v135, v135
	s_nop 0
	global_store_short v9, v10, s[8:9] offset:1536
	s_nop 1
.Lcp_done:
.LBB0_350:
.LBB0_477:
	s_waitcnt vmcnt(0)
	s_waitcnt lgkmcnt(0)
	s_barrier
	s_and_saveexec_b64 s[0:1], s[58:59]
	s_cbranch_execz .LBB0_529
	v_mov_b32_e32 v0, 0
	s_waitcnt vmcnt(0) expcnt(0) lgkmcnt(0)
	ds_read_b32 v2, v0 offset:16
	ds_read_b32 v1, v0 offset:20
	s_waitcnt lgkmcnt(1)
	v_cmp_ne_u32_e32 vcc, 0, v2
	s_cbranch_vccnz .LBB0_493
	s_add_u32 s2, s86, 0xec80400
	s_addc_u32 s3, s87, 0
	s_add_u32 s4, s86, 0xec80600
	s_addc_u32 s5, s87, 0
	s_add_u32 s6, s86, 0xec80700
	s_addc_u32 s7, s87, 0
	s_add_u32 s8, s86, 0xec80800
	s_addc_u32 s9, s87, 0
	s_add_u32 s10, s86, 0xec80900
	s_addc_u32 s11, s87, 0
	s_add_u32 s12, s86, 0xec80a00
	s_addc_u32 s13, s87, 0
	s_add_u32 s14, s86, 0xec80b00
	s_addc_u32 s15, s87, 0
	s_add_u32 s16, s86, 0xec80c00
	s_addc_u32 s17, s87, 0
	s_add_u32 s18, s86, 0xec80d00
	s_addc_u32 s19, s87, 0
	s_add_u32 s20, s86, 0xec80e00
	s_addc_u32 s21, s87, 0
	s_add_u32 s22, s86, 0xec80f00
	s_addc_u32 s23, s87, 0
	s_add_u32 s24, s86, 0xec81000
	s_addc_u32 s25, s87, 0
	s_add_u32 s26, s86, 0xec81100
	s_addc_u32 s27, s87, 0
	s_add_u32 s28, s86, 0xec81200
	s_addc_u32 s29, s87, 0
	s_add_u32 s30, s86, 0xec81300
	s_addc_u32 s31, s87, 0
	s_add_u32 s34, s86, 0xec81400
	s_addc_u32 s35, s87, 0
	s_mul_i32 s44, s55, s60
	s_add_u32 s36, s86, 0xec81500
	s_mul_i32 s44, s44, s54
	s_addc_u32 s37, s87, 0
	s_mov_b32 s45, 1
	s_branch .LBB0_481
